# GEMM K-loops: 14-16 of 16 LDS-DMA loads per iteration in SGPR-base form (base + 0x80 advanced by SALU, spare pair s[100:101]); no instruction offsets on LDS-DMA
# baseline (speedup 1.0000x reference)
; #define PG8_STAGE(bufoff, gbase, voff) do { _Pragma("unroll") for (int _i = 0; _i < 2; ++_i) \
;         __builtin_amdgcn_global_load_lds((const unsigned*)((const char*)(gbase) + (voff)[_i]), (PG8_LAS unsigned*)(lds + (bufoff) + ldsw + _i * 8192), 16, 0, 0); } while (0)
; #define PG8_LDA(dst, b, h) do { _Pragma("unroll") for (int m = 0; m < 4; ++m) _Pragma("unroll") for (int k = 0; k < 2; ++k) dst[m][k] = *(const PG8_LAS bf16x8*)(lds + PG8_SA(b, h) + aoff + m * 2048 + k * 1024); } while (0)
; #define PG8_LDB(dst, b, h) do { _Pragma("unroll") for (int n = 0; n < 2; ++n) _Pragma("unroll") for (int k = 0; k < 2; ++k) dst[n][k] = *(const PG8_LAS bf16x8*)(lds + PG8_SB(b, h) + boff + n * 2048 + k * 1024); } while (0)
; #define PG8_MMA(ai, bj, At, Bt) do { __builtin_amdgcn_s_setprio(1); _Pragma("unroll") for (int m = 0; m < 4; ++m) _Pragma("unroll") for (int n = 0; n < 2; ++n) _Pragma("unroll") for (int k = 0; k < 2; ++k) \
;         acc[ai][bj][m][n] = __builtin_amdgcn_mfma_f32_16x16x32_bf16(Bt[n][k], At[m][k], acc[ai][bj][m][n], 0, 0, 0); __builtin_amdgcn_s_setprio(0); } while (0)
; #define PG8_WAIT_V(n) asm volatile("s_waitcnt vmcnt(" #n ")" ::: "memory")
; #define PG8_WAIT_L(n) asm volatile("s_waitcnt lgkmcnt(" #n ")" ::: "memory")
; template <class Epi, class Sched, bool ALIGN_EPI = false, bool SP2 = false>
; __device__ __forceinline__ void gemm_phase(PG8_LAS unsigned char* lds, const Gemm g, const Sched& S, const Epi& E, int tid_in) {
;     ...
;             const bool last = (t == nt - 2);
;             const char* a1 = cA + (size_t)(t + 1) * kstep;
;             const char* a2 = last ? nA : cA + (size_t)(t + 2) * kstep; const char* b2 = last ? nB : cB + (size_t)(t + 2) * kstep;
;             const char* a3 = a2 + kstep; const char* b3 = b2 + kstep;
;             if (last && has_next) S.a_ready(nxt);
;             if constexpr (SP2) {
;             PG8_LDB(B0, 0, 0); PG8_LDB(B1, 0, 1); PG8_SCHED; PG8_LDA(At, 0, 0); PG8_STAGE(PG8_SA(1, 1), a1 + hstepA, voffA);
;             PG8_WAIT_V(8); PG8_WAIT_L(0); PG8_BAR; PG8_MMA(0, 0, At, B0); PG8_MMA(0, 1, At, B1); PG8_BAR; PG8_SCHED;
;             PG8_LDA(At, 0, 1); PG8_STAGE(PG8_SB(0, 0), b2, voffB); PG8_STAGE(PG8_SB(0, 1), b2 + hstep, voffB); PG8_STAGE(PG8_SA(0, 0), a2, voffA);
;             PG8_WAIT_V(8); PG8_WAIT_L(0); PG8_BAR; PG8_MMA(1, 0, At, B0); PG8_MMA(1, 1, At, B1); PG8_BAR; PG8_SCHED;
.LBB0_204:
	s_add_u32 s10, s2, 0xfffc0080
	s_addc_u32 s11, s3, -1
	s_add_i32 s28, 0, 0x10000
	s_cmp_eq_u32 s27, 12
	s_cselect_b32 s13, s15, s11
	s_cselect_b32 s12, s20, s10
	v_add_u32_e32 v156, s28, v159
	s_cselect_b32 s11, s21, s26
	s_cselect_b32 s10, s24, s25
	s_add_i32 s52, 0, 0x14000
	ds_read_b128 v[144:147], v156
	ds_read_b128 v[148:151], v156 offset:1024
	ds_read_b128 v[152:155], v156 offset:2048
	ds_read_b128 v[162:165], v156 offset:3072
	v_add_u32_e32 v156, s52, v159
	ds_read_b128 v[166:169], v156
	ds_read_b128 v[170:173], v156 offset:1024
	ds_read_b128 v[174:177], v156 offset:2048
	ds_read_b128 v[178:181], v156 offset:3072
	s_add_i32 m0, s35, 0xc000
	ds_read_b128 v[182:185], v160
	ds_read_b128 v[186:189], v160 offset:1024
	ds_read_b128 v[200:203], v160 offset:2048
	ds_read_b128 v[204:207], v160 offset:3072
	ds_read_b128 v[208:211], v160 offset:4096
	ds_read_b128 v[212:215], v160 offset:5120
	ds_read_b128 v[216:219], v160 offset:6144
	ds_read_b128 v[226:229], v160 offset:7168
	global_load_lds_dwordx4 v142, s[2:3]
	s_add_i32 m0, s35, 0xe000
	s_nop 0
	global_load_lds_dwordx4 v140, s[2:3]
	s_waitcnt vmcnt(8)
	s_waitcnt lgkmcnt(0)
	s_barrier
	s_setprio 1
	s_waitcnt lgkmcnt(0)
	v_mfma_f32_16x16x32_bf16 v[124:127], v[144:147], v[182:185], v[124:127]
	v_mfma_f32_16x16x32_bf16 v[120:123], v[152:155], v[182:185], v[120:123]
	v_mfma_f32_16x16x32_bf16 v[108:111], v[144:147], v[200:203], v[108:111]
	v_mfma_f32_16x16x32_bf16 v[104:107], v[152:155], v[200:203], v[104:107]
	v_mfma_f32_16x16x32_bf16 v[92:95], v[144:147], v[208:211], v[92:95]
	v_mfma_f32_16x16x32_bf16 v[88:91], v[152:155], v[208:211], v[88:91]
	v_mfma_f32_16x16x32_bf16 v[76:79], v[144:147], v[216:219], v[76:79]
	v_mfma_f32_16x16x32_bf16 v[72:75], v[152:155], v[216:219], v[72:75]
	v_mfma_f32_16x16x32_bf16 v[124:127], v[148:151], v[186:189], v[124:127]
	v_mfma_f32_16x16x32_bf16 v[120:123], v[162:165], v[186:189], v[120:123]
	v_mfma_f32_16x16x32_bf16 v[108:111], v[148:151], v[204:207], v[108:111]
	v_mfma_f32_16x16x32_bf16 v[104:107], v[162:165], v[204:207], v[104:107]
	v_mfma_f32_16x16x32_bf16 v[92:95], v[148:151], v[212:215], v[92:95]
	v_mfma_f32_16x16x32_bf16 v[88:91], v[162:165], v[212:215], v[88:91]
	v_mfma_f32_16x16x32_bf16 v[76:79], v[148:151], v[226:229], v[76:79]
	v_mfma_f32_16x16x32_bf16 v[72:75], v[162:165], v[226:229], v[72:75]
	s_setprio 0
	s_setprio 1
	v_mfma_f32_16x16x32_bf16 v[116:119], v[166:169], v[182:185], v[116:119]
	v_mfma_f32_16x16x32_bf16 v[112:115], v[174:177], v[182:185], v[112:115]
	v_mfma_f32_16x16x32_bf16 v[100:103], v[166:169], v[200:203], v[100:103]
	v_mfma_f32_16x16x32_bf16 v[96:99], v[174:177], v[200:203], v[96:99]
	v_mfma_f32_16x16x32_bf16 v[84:87], v[166:169], v[208:211], v[84:87]
	v_mfma_f32_16x16x32_bf16 v[80:83], v[174:177], v[208:211], v[80:83]
	v_mfma_f32_16x16x32_bf16 v[68:71], v[166:169], v[216:219], v[68:71]
	v_mfma_f32_16x16x32_bf16 v[64:67], v[174:177], v[216:219], v[64:67]
	v_mfma_f32_16x16x32_bf16 v[116:119], v[170:173], v[186:189], v[116:119]
	v_mfma_f32_16x16x32_bf16 v[112:115], v[178:181], v[186:189], v[112:115]
	v_mfma_f32_16x16x32_bf16 v[100:103], v[170:173], v[204:207], v[100:103]
	v_mfma_f32_16x16x32_bf16 v[96:99], v[178:181], v[204:207], v[96:99]
	v_mfma_f32_16x16x32_bf16 v[84:87], v[170:173], v[212:215], v[84:87]
	v_mfma_f32_16x16x32_bf16 v[80:83], v[178:181], v[212:215], v[80:83]
	v_mfma_f32_16x16x32_bf16 v[68:71], v[170:173], v[226:229], v[68:71]
	v_mfma_f32_16x16x32_bf16 v[64:67], v[178:181], v[226:229], v[64:67]
	s_setprio 0
	s_barrier
	s_add_i32 s28, s28, s34
	s_mov_b32 m0, s28
	ds_read_b128 v[182:185], v160 offset:16384
	ds_read_b128 v[186:189], v160 offset:17408
	ds_read_b128 v[200:203], v160 offset:18432
	ds_read_b128 v[204:207], v160 offset:19456
	ds_read_b128 v[208:211], v160 offset:20480
	ds_read_b128 v[212:215], v160 offset:21504
	ds_read_b128 v[216:219], v160 offset:22528
	ds_read_b128 v[226:229], v160 offset:23552
	global_load_lds_dwordx4 v132, s[10:11]
	s_add_i32 m0, s28, 0x2000
	s_add_u32 s28, s10, 0x40000
	s_addc_u32 s29, s11, 0
	s_add_i32 s52, s52, s34
	global_load_lds_dwordx4 v128, s[10:11]
	s_mov_b32 m0, s52
	s_mov_b64 s[100:101], s[12:13]
	global_load_lds_dwordx4 v132, s[28:29]
	s_add_i32 m0, s52, 0x2000
	s_nop 0
	global_load_lds_dwordx4 v128, s[28:29]
	s_mov_b32 m0, s35
	s_nop 0
	global_load_lds_dwordx4 v134, s[100:101]
	s_mov_b32 m0, s38
	s_nop 0
	global_load_lds_dwordx4 v130, s[100:101]
	s_waitcnt vmcnt(8)
	s_waitcnt lgkmcnt(0)
	s_barrier
	s_setprio 1
	s_waitcnt lgkmcnt(0)
	v_mfma_f32_16x16x32_bf16 v[60:63], v[144:147], v[182:185], v[60:63]
	v_mfma_f32_16x16x32_bf16 v[56:59], v[152:155], v[182:185], v[56:59]
	v_mfma_f32_16x16x32_bf16 v[44:47], v[144:147], v[200:203], v[44:47]
	v_mfma_f32_16x16x32_bf16 v[40:43], v[152:155], v[200:203], v[40:43]
	v_mfma_f32_16x16x32_bf16 v[28:31], v[144:147], v[208:211], v[28:31]
	v_mfma_f32_16x16x32_bf16 v[24:27], v[152:155], v[208:211], v[24:27]
	v_mfma_f32_16x16x32_bf16 v[12:15], v[144:147], v[216:219], v[12:15]
	v_mfma_f32_16x16x32_bf16 v[8:11], v[152:155], v[216:219], v[8:11]
	v_mfma_f32_16x16x32_bf16 v[60:63], v[148:151], v[186:189], v[60:63]
	v_mfma_f32_16x16x32_bf16 v[56:59], v[162:165], v[186:189], v[56:59]
	v_mfma_f32_16x16x32_bf16 v[44:47], v[148:151], v[204:207], v[44:47]
	v_mfma_f32_16x16x32_bf16 v[40:43], v[162:165], v[204:207], v[40:43]
	v_mfma_f32_16x16x32_bf16 v[28:31], v[148:151], v[212:215], v[28:31]
	v_mfma_f32_16x16x32_bf16 v[24:27], v[162:165], v[212:215], v[24:27]
	v_mfma_f32_16x16x32_bf16 v[12:15], v[148:151], v[226:229], v[12:15]
	v_mfma_f32_16x16x32_bf16 v[8:11], v[162:165], v[226:229], v[8:11]
	s_setprio 0
	s_setprio 1
	v_mfma_f32_16x16x32_bf16 v[52:55], v[166:169], v[182:185], v[52:55]
	v_mfma_f32_16x16x32_bf16 v[48:51], v[174:177], v[182:185], v[48:51]
	v_mfma_f32_16x16x32_bf16 v[36:39], v[166:169], v[200:203], v[36:39]
	v_mfma_f32_16x16x32_bf16 v[32:35], v[174:177], v[200:203], v[32:35]
	v_mfma_f32_16x16x32_bf16 v[20:23], v[166:169], v[208:211], v[20:23]
	v_mfma_f32_16x16x32_bf16 v[16:19], v[174:177], v[208:211], v[16:19]
	v_mfma_f32_16x16x32_bf16 v[4:7], v[166:169], v[216:219], v[4:7]
	v_mfma_f32_16x16x32_bf16 v[0:3], v[174:177], v[216:219], v[0:3]
	v_mfma_f32_16x16x32_bf16 v[52:55], v[170:173], v[186:189], v[52:55]
	v_mfma_f32_16x16x32_bf16 v[48:51], v[178:181], v[186:189], v[48:51]
	v_mfma_f32_16x16x32_bf16 v[36:39], v[170:173], v[204:207], v[36:39]
	v_mfma_f32_16x16x32_bf16 v[32:35], v[178:181], v[204:207], v[32:35]
	v_mfma_f32_16x16x32_bf16 v[20:23], v[170:173], v[212:215], v[20:23]
	v_mfma_f32_16x16x32_bf16 v[16:19], v[178:181], v[212:215], v[16:19]
	v_mfma_f32_16x16x32_bf16 v[4:7], v[170:173], v[226:229], v[4:7]
	v_mfma_f32_16x16x32_bf16 v[0:3], v[178:181], v[226:229], v[0:3]
	s_setprio 0
	s_barrier
; #define PG8_STAGE(bufoff, gbase, voff) do { _Pragma("unroll") for (int _i = 0; _i < 2; ++_i) \
;         __builtin_amdgcn_global_load_lds((const unsigned*)((const char*)(gbase) + (voff)[_i]), (PG8_LAS unsigned*)(lds + (bufoff) + ldsw + _i * 8192), 16, 0, 0); } while (0)
; #define PG8_LDA(dst, b, h) do { _Pragma("unroll") for (int m = 0; m < 4; ++m) _Pragma("unroll") for (int k = 0; k < 2; ++k) dst[m][k] = *(const PG8_LAS bf16x8*)(lds + PG8_SA(b, h) + aoff + m * 2048 + k * 1024); } while (0)
; #define PG8_LDB(dst, b, h) do { _Pragma("unroll") for (int n = 0; n < 2; ++n) _Pragma("unroll") for (int k = 0; k < 2; ++k) dst[n][k] = *(const PG8_LAS bf16x8*)(lds + PG8_SB(b, h) + boff + n * 2048 + k * 1024); } while (0)
; #define PG8_MMA(ai, bj, At, Bt) do { __builtin_amdgcn_s_setprio(1); _Pragma("unroll") for (int m = 0; m < 4; ++m) _Pragma("unroll") for (int n = 0; n < 2; ++n) _Pragma("unroll") for (int k = 0; k < 2; ++k) \
;         acc[ai][bj][m][n] = __builtin_amdgcn_mfma_f32_16x16x32_bf16(Bt[n][k], At[m][k], acc[ai][bj][m][n], 0, 0, 0); __builtin_amdgcn_s_setprio(0); } while (0)
; #define PG8_WAIT_V(n) asm volatile("s_waitcnt vmcnt(" #n ")" ::: "memory")
; #define PG8_WAIT_L(n) asm volatile("s_waitcnt lgkmcnt(" #n ")" ::: "memory")
; #define PG8_BAR __builtin_amdgcn_s_barrier()
; #define PG8_SCHED __builtin_amdgcn_sched_barrier(0)
; template <class Epi, class Sched, bool ALIGN_EPI = false, bool SP2 = false>
; __device__ __forceinline__ void gemm_phase(PG8_LAS unsigned char* lds, const Gemm g, const Sched& S, const Epi& E, int tid_in) {
;     ...
;             PG8_LDB(B0, 1, 0); PG8_LDB(B1, 1, 1); PG8_SCHED; PG8_LDA(At, 1, 0); PG8_STAGE(PG8_SA(0, 1), a2 + hstepA, voffA);
;             PG8_WAIT_V(8); PG8_WAIT_L(0); PG8_BAR; PG8_MMA(0, 0, At, B0); PG8_MMA(0, 1, At, B1); PG8_BAR; PG8_SCHED;
;             PG8_LDA(At, 1, 1); PG8_STAGE(PG8_SB(1, 0), b3, voffB); PG8_STAGE(PG8_SB(1, 1), b3 + hstep, voffB); PG8_STAGE(PG8_SA(1, 0), a3, voffA);
;             PG8_WAIT_V(8); PG8_WAIT_L(0); PG8_BAR; PG8_MMA(1, 0, At, B0); PG8_MMA(1, 1, At, B1); PG8_BAR; PG8_SCHED;
	s_add_i32 s28, 0, 0x18000
	v_add_u32_e32 v161, s28, v159
	s_add_i32 s29, 0, 0x1c000
	ds_read_b128 v[144:147], v161
	ds_read_b128 v[148:151], v161 offset:1024
	ds_read_b128 v[152:155], v161 offset:2048
	ds_read_b128 v[162:165], v161 offset:3072
	v_add_u32_e32 v161, s29, v159
	ds_read_b128 v[166:169], v161
	ds_read_b128 v[170:173], v161 offset:1024
	ds_read_b128 v[174:177], v161 offset:2048
	ds_read_b128 v[178:181], v161 offset:3072
	s_add_u32 s12, s12, 0x40000
	s_addc_u32 s13, s13, 0
	s_mov_b32 m0, s77
	ds_read_b128 v[182:185], v160 offset:32768
	ds_read_b128 v[186:189], v160 offset:33792
	ds_read_b128 v[200:203], v160 offset:34816
	ds_read_b128 v[204:207], v160 offset:35840
	ds_read_b128 v[208:211], v160 offset:36864
	ds_read_b128 v[212:215], v160 offset:37888
	ds_read_b128 v[216:219], v160 offset:38912
	ds_read_b128 v[226:229], v160 offset:39936
	global_load_lds_dwordx4 v134, s[12:13]
	s_mov_b32 m0, s78
	s_nop 0
	global_load_lds_dwordx4 v130, s[12:13]
	s_waitcnt vmcnt(8)
	s_waitcnt lgkmcnt(0)
	s_barrier
	s_setprio 1
	s_waitcnt lgkmcnt(0)
	v_mfma_f32_16x16x32_bf16 v[124:127], v[144:147], v[182:185], v[124:127]
	v_mfma_f32_16x16x32_bf16 v[120:123], v[152:155], v[182:185], v[120:123]
	v_mfma_f32_16x16x32_bf16 v[108:111], v[144:147], v[200:203], v[108:111]
	v_mfma_f32_16x16x32_bf16 v[104:107], v[152:155], v[200:203], v[104:107]
	v_mfma_f32_16x16x32_bf16 v[92:95], v[144:147], v[208:211], v[92:95]
	v_mfma_f32_16x16x32_bf16 v[88:91], v[152:155], v[208:211], v[88:91]
	v_mfma_f32_16x16x32_bf16 v[76:79], v[144:147], v[216:219], v[76:79]
	v_mfma_f32_16x16x32_bf16 v[72:75], v[152:155], v[216:219], v[72:75]
	v_mfma_f32_16x16x32_bf16 v[124:127], v[148:151], v[186:189], v[124:127]
	v_mfma_f32_16x16x32_bf16 v[120:123], v[162:165], v[186:189], v[120:123]
	v_mfma_f32_16x16x32_bf16 v[108:111], v[148:151], v[204:207], v[108:111]
	v_mfma_f32_16x16x32_bf16 v[104:107], v[162:165], v[204:207], v[104:107]
	v_mfma_f32_16x16x32_bf16 v[92:95], v[148:151], v[212:215], v[92:95]
	v_mfma_f32_16x16x32_bf16 v[88:91], v[162:165], v[212:215], v[88:91]
	v_mfma_f32_16x16x32_bf16 v[76:79], v[148:151], v[226:229], v[76:79]
	v_mfma_f32_16x16x32_bf16 v[72:75], v[162:165], v[226:229], v[72:75]
	s_setprio 0
	s_setprio 1
	v_mfma_f32_16x16x32_bf16 v[116:119], v[166:169], v[182:185], v[116:119]
	v_mfma_f32_16x16x32_bf16 v[112:115], v[174:177], v[182:185], v[112:115]
	v_mfma_f32_16x16x32_bf16 v[100:103], v[166:169], v[200:203], v[100:103]
	v_mfma_f32_16x16x32_bf16 v[96:99], v[174:177], v[200:203], v[96:99]
	v_mfma_f32_16x16x32_bf16 v[84:87], v[166:169], v[208:211], v[84:87]
	v_mfma_f32_16x16x32_bf16 v[80:83], v[174:177], v[208:211], v[80:83]
	v_mfma_f32_16x16x32_bf16 v[68:71], v[166:169], v[216:219], v[68:71]
	v_mfma_f32_16x16x32_bf16 v[64:67], v[174:177], v[216:219], v[64:67]
	v_mfma_f32_16x16x32_bf16 v[116:119], v[170:173], v[186:189], v[116:119]
	v_mfma_f32_16x16x32_bf16 v[112:115], v[178:181], v[186:189], v[112:115]
	v_mfma_f32_16x16x32_bf16 v[100:103], v[170:173], v[204:207], v[100:103]
	v_mfma_f32_16x16x32_bf16 v[96:99], v[178:181], v[204:207], v[96:99]
	v_mfma_f32_16x16x32_bf16 v[84:87], v[170:173], v[212:215], v[84:87]
	v_mfma_f32_16x16x32_bf16 v[80:83], v[178:181], v[212:215], v[80:83]
	v_mfma_f32_16x16x32_bf16 v[68:71], v[170:173], v[226:229], v[68:71]
	v_mfma_f32_16x16x32_bf16 v[64:67], v[178:181], v[226:229], v[64:67]
	s_setprio 0
	s_barrier
	s_add_i32 s12, s28, s34
	s_mov_b32 m0, s12
	ds_read_b128 v[182:185], v160 offset:49152
	ds_read_b128 v[186:189], v160 offset:50176
	ds_read_b128 v[200:203], v160 offset:51200
	ds_read_b128 v[204:207], v160 offset:52224
	ds_read_b128 v[208:211], v160 offset:53248
	ds_read_b128 v[212:215], v160 offset:54272
	ds_read_b128 v[216:219], v160 offset:55296
	ds_read_b128 v[226:229], v160 offset:56320
	s_add_u32 s10, s10, 0x80
	s_addc_u32 s11, s11, 0
	global_load_lds_dwordx4 v132, s[10:11]
	s_add_i32 m0, s12, 0x2000
	s_nop 0
	global_load_lds_dwordx4 v128, s[10:11]
	s_add_u32 s10, s10, 0x40000
	s_addc_u32 s11, s11, 0
	s_add_i32 s12, s29, s34
	s_mov_b32 m0, s12
	s_nop 0
	global_load_lds_dwordx4 v132, s[10:11]
	s_add_i32 m0, s12, 0x2000
	s_nop 0
	global_load_lds_dwordx4 v128, s[10:11]
	s_mov_b32 m0, s83
	s_nop 0
	s_add_u32 s100, s100, 0x80
	s_addc_u32 s101, s101, 0
	global_load_lds_dwordx4 v134, s[100:101]
	s_mov_b32 m0, s84
	s_nop 0
	global_load_lds_dwordx4 v130, s[100:101]
	s_waitcnt vmcnt(8)
	s_waitcnt lgkmcnt(0)
	s_barrier
	s_setprio 1
	s_waitcnt lgkmcnt(0)
	v_mfma_f32_16x16x32_bf16 v[60:63], v[144:147], v[182:185], v[60:63]
	v_mfma_f32_16x16x32_bf16 v[56:59], v[152:155], v[182:185], v[56:59]
	v_mfma_f32_16x16x32_bf16 v[44:47], v[144:147], v[200:203], v[44:47]
	v_mfma_f32_16x16x32_bf16 v[40:43], v[152:155], v[200:203], v[40:43]
	v_mfma_f32_16x16x32_bf16 v[28:31], v[144:147], v[208:211], v[28:31]
	v_mfma_f32_16x16x32_bf16 v[24:27], v[152:155], v[208:211], v[24:27]
	v_mfma_f32_16x16x32_bf16 v[12:15], v[144:147], v[216:219], v[12:15]
	v_mfma_f32_16x16x32_bf16 v[8:11], v[152:155], v[216:219], v[8:11]
	v_mfma_f32_16x16x32_bf16 v[60:63], v[148:151], v[186:189], v[60:63]
	v_mfma_f32_16x16x32_bf16 v[56:59], v[162:165], v[186:189], v[56:59]
	v_mfma_f32_16x16x32_bf16 v[44:47], v[148:151], v[204:207], v[44:47]
	v_mfma_f32_16x16x32_bf16 v[40:43], v[162:165], v[204:207], v[40:43]
	v_mfma_f32_16x16x32_bf16 v[28:31], v[148:151], v[212:215], v[28:31]
	v_mfma_f32_16x16x32_bf16 v[24:27], v[162:165], v[212:215], v[24:27]
	v_mfma_f32_16x16x32_bf16 v[12:15], v[148:151], v[226:229], v[12:15]
	v_mfma_f32_16x16x32_bf16 v[8:11], v[162:165], v[226:229], v[8:11]
	s_setprio 0
	s_setprio 1
	v_mfma_f32_16x16x32_bf16 v[52:55], v[166:169], v[182:185], v[52:55]
	v_mfma_f32_16x16x32_bf16 v[48:51], v[174:177], v[182:185], v[48:51]
	v_mfma_f32_16x16x32_bf16 v[36:39], v[166:169], v[200:203], v[36:39]
	v_mfma_f32_16x16x32_bf16 v[32:35], v[174:177], v[200:203], v[32:35]
	v_mfma_f32_16x16x32_bf16 v[20:23], v[166:169], v[208:211], v[20:23]
	v_mfma_f32_16x16x32_bf16 v[16:19], v[174:177], v[208:211], v[16:19]
	v_mfma_f32_16x16x32_bf16 v[4:7], v[166:169], v[216:219], v[4:7]
	v_mfma_f32_16x16x32_bf16 v[0:3], v[174:177], v[216:219], v[0:3]
	v_mfma_f32_16x16x32_bf16 v[52:55], v[170:173], v[186:189], v[52:55]
	v_mfma_f32_16x16x32_bf16 v[48:51], v[178:181], v[186:189], v[48:51]
	v_mfma_f32_16x16x32_bf16 v[36:39], v[170:173], v[204:207], v[36:39]
	v_mfma_f32_16x16x32_bf16 v[32:35], v[178:181], v[204:207], v[32:35]
	v_mfma_f32_16x16x32_bf16 v[20:23], v[170:173], v[212:215], v[20:23]
	v_mfma_f32_16x16x32_bf16 v[16:19], v[178:181], v[212:215], v[16:19]
	v_mfma_f32_16x16x32_bf16 v[4:7], v[170:173], v[226:229], v[4:7]
	v_mfma_f32_16x16x32_bf16 v[0:3], v[178:181], v[226:229], v[0:3]
	s_setprio 0
	s_barrier
	s_add_i32 s27, s27, 2
	s_add_u32 s25, s25, 0x100
	s_addc_u32 s26, s26, 0
	s_add_u32 s2, s2, 0x100
	s_addc_u32 s3, s3, 0
	s_cmp_gt_u32 s27, 13
	s_cbranch_scc0 .LBB0_204
	s_and_b64 vcc, exec, s[62:63]
	s_cbranch_vccz .LBB0_207
	s_barrier

; #define PG8_STAGE(bufoff, gbase, voff) do { _Pragma("unroll") for (int _i = 0; _i < 2; ++_i) \
;         __builtin_amdgcn_global_load_lds((const unsigned*)((const char*)(gbase) + (voff)[_i]), (PG8_LAS unsigned*)(lds + (bufoff) + ldsw + _i * 8192), 16, 0, 0); } while (0)
; #define PG8_LDA(dst, b, h) do { _Pragma("unroll") for (int m = 0; m < 4; ++m) _Pragma("unroll") for (int k = 0; k < 2; ++k) dst[m][k] = *(const PG8_LAS bf16x8*)(lds + PG8_SA(b, h) + aoff + m * 2048 + k * 1024); } while (0)
; #define PG8_LDB(dst, b, h) do { _Pragma("unroll") for (int n = 0; n < 2; ++n) _Pragma("unroll") for (int k = 0; k < 2; ++k) dst[n][k] = *(const PG8_LAS bf16x8*)(lds + PG8_SB(b, h) + boff + n * 2048 + k * 1024); } while (0)
; #define PG8_MMA(ai, bj, At, Bt) do { __builtin_amdgcn_s_setprio(1); _Pragma("unroll") for (int m = 0; m < 4; ++m) _Pragma("unroll") for (int n = 0; n < 2; ++n) _Pragma("unroll") for (int k = 0; k < 2; ++k) \
;         acc[ai][bj][m][n] = __builtin_amdgcn_mfma_f32_16x16x32_bf16(Bt[n][k], At[m][k], acc[ai][bj][m][n], 0, 0, 0); __builtin_amdgcn_s_setprio(0); } while (0)
; #define PG8_WAIT_V(n) asm volatile("s_waitcnt vmcnt(" #n ")" ::: "memory")
; #define PG8_WAIT_L(n) asm volatile("s_waitcnt lgkmcnt(" #n ")" ::: "memory")
; template <class Epi, class Sched, bool ALIGN_EPI = false, bool SP2 = false>
; __device__ __forceinline__ void gemm_phase(PG8_LAS unsigned char* lds, const Gemm g, const Sched& S, const Epi& E, int tid_in) {
;     ...
;             const bool last = (t == nt - 2);
;             const char* a1 = cA + (size_t)(t + 1) * kstep;
;             const char* a2 = last ? nA : cA + (size_t)(t + 2) * kstep; const char* b2 = last ? nB : cB + (size_t)(t + 2) * kstep;
;             const char* a3 = a2 + kstep; const char* b3 = b2 + kstep;
;             if (last && has_next) S.a_ready(nxt);
;             if constexpr (SP2) {
;             PG8_LDB(B0, 0, 0); PG8_LDB(B1, 0, 1); PG8_SCHED; PG8_LDA(At, 0, 0); PG8_STAGE(PG8_SA(1, 1), a1 + hstepA, voffA);
;             PG8_WAIT_V(8); PG8_WAIT_L(0); PG8_BAR; PG8_MMA(0, 0, At, B0); PG8_MMA(0, 1, At, B1); PG8_BAR; PG8_SCHED;
;             PG8_LDA(At, 0, 1); PG8_STAGE(PG8_SB(0, 0), b2, voffB); PG8_STAGE(PG8_SB(0, 1), b2 + hstep, voffB); PG8_STAGE(PG8_SA(0, 0), a2, voffA);
;             PG8_WAIT_V(8); PG8_WAIT_L(0); PG8_BAR; PG8_MMA(1, 0, At, B0); PG8_MMA(1, 1, At, B1); PG8_BAR; PG8_SCHED;
.LBB0_526:
	s_add_u32 s12, s2, 0xfffc0080
	s_addc_u32 s13, s3, -1
	s_add_i32 s66, 0, 0x10000
	s_cmp_eq_u32 s65, 12
	s_cselect_b32 s15, s45, s13
	s_cselect_b32 s14, s46, s12
	v_add_u32_e32 v148, s66, v151
	s_cselect_b32 s13, s29, s64
	s_cselect_b32 s12, s47, s51
	s_add_i32 s68, 0, 0x14000
	ds_read_b128 v[140:143], v148
	ds_read_b128 v[144:147], v148 offset:1024
	ds_read_b128 v[160:163], v148 offset:2048
	ds_read_b128 v[164:167], v148 offset:3072
	v_add_u32_e32 v148, s68, v151
	ds_read_b128 v[168:171], v148
	ds_read_b128 v[172:175], v148 offset:1024
	ds_read_b128 v[176:179], v148 offset:2048
	ds_read_b128 v[180:183], v148 offset:3072
	s_add_i32 m0, s56, 0xc000
	ds_read_b128 v[184:187], v156
	ds_read_b128 v[200:203], v156 offset:1024
	ds_read_b128 v[204:207], v156 offset:2048
	ds_read_b128 v[208:211], v156 offset:3072
	ds_read_b128 v[212:215], v156 offset:4096
	ds_read_b128 v[216:219], v156 offset:5120
	ds_read_b128 v[226:229], v156 offset:6144
	ds_read_b128 v[230:233], v156 offset:7168
	global_load_lds_dwordx4 v138, s[2:3]
	s_add_i32 m0, s56, 0xe000
	s_nop 0
	global_load_lds_dwordx4 v136, s[2:3]
	s_waitcnt vmcnt(8)
	s_waitcnt lgkmcnt(0)
	s_barrier
	s_setprio 1
	s_waitcnt lgkmcnt(0)
	v_mfma_f32_16x16x32_bf16 v[124:127], v[140:143], v[184:187], v[124:127]
	v_mfma_f32_16x16x32_bf16 v[120:123], v[160:163], v[184:187], v[120:123]
	v_mfma_f32_16x16x32_bf16 v[108:111], v[140:143], v[204:207], v[108:111]
	v_mfma_f32_16x16x32_bf16 v[104:107], v[160:163], v[204:207], v[104:107]
	v_mfma_f32_16x16x32_bf16 v[92:95], v[140:143], v[212:215], v[92:95]
	v_mfma_f32_16x16x32_bf16 v[88:91], v[160:163], v[212:215], v[88:91]
	v_mfma_f32_16x16x32_bf16 v[76:79], v[140:143], v[226:229], v[76:79]
	v_mfma_f32_16x16x32_bf16 v[72:75], v[160:163], v[226:229], v[72:75]
	v_mfma_f32_16x16x32_bf16 v[124:127], v[144:147], v[200:203], v[124:127]
	v_mfma_f32_16x16x32_bf16 v[120:123], v[164:167], v[200:203], v[120:123]
	v_mfma_f32_16x16x32_bf16 v[108:111], v[144:147], v[208:211], v[108:111]
	v_mfma_f32_16x16x32_bf16 v[104:107], v[164:167], v[208:211], v[104:107]
	v_mfma_f32_16x16x32_bf16 v[92:95], v[144:147], v[216:219], v[92:95]
	v_mfma_f32_16x16x32_bf16 v[88:91], v[164:167], v[216:219], v[88:91]
	v_mfma_f32_16x16x32_bf16 v[76:79], v[144:147], v[230:233], v[76:79]
	v_mfma_f32_16x16x32_bf16 v[72:75], v[164:167], v[230:233], v[72:75]
	s_setprio 0
	s_setprio 1
	v_mfma_f32_16x16x32_bf16 v[116:119], v[168:171], v[184:187], v[116:119]
	v_mfma_f32_16x16x32_bf16 v[112:115], v[176:179], v[184:187], v[112:115]
	v_mfma_f32_16x16x32_bf16 v[100:103], v[168:171], v[204:207], v[100:103]
	v_mfma_f32_16x16x32_bf16 v[96:99], v[176:179], v[204:207], v[96:99]
	v_mfma_f32_16x16x32_bf16 v[84:87], v[168:171], v[212:215], v[84:87]
	v_mfma_f32_16x16x32_bf16 v[80:83], v[176:179], v[212:215], v[80:83]
	v_mfma_f32_16x16x32_bf16 v[68:71], v[168:171], v[226:229], v[68:71]
	v_mfma_f32_16x16x32_bf16 v[64:67], v[176:179], v[226:229], v[64:67]
	v_mfma_f32_16x16x32_bf16 v[116:119], v[172:175], v[200:203], v[116:119]
	v_mfma_f32_16x16x32_bf16 v[112:115], v[180:183], v[200:203], v[112:115]
	v_mfma_f32_16x16x32_bf16 v[100:103], v[172:175], v[208:211], v[100:103]
	v_mfma_f32_16x16x32_bf16 v[96:99], v[180:183], v[208:211], v[96:99]
	v_mfma_f32_16x16x32_bf16 v[84:87], v[172:175], v[216:219], v[84:87]
	v_mfma_f32_16x16x32_bf16 v[80:83], v[180:183], v[216:219], v[80:83]
	v_mfma_f32_16x16x32_bf16 v[68:71], v[172:175], v[230:233], v[68:71]
	v_mfma_f32_16x16x32_bf16 v[64:67], v[180:183], v[230:233], v[64:67]
	s_setprio 0
	s_barrier
	s_add_i32 s66, s66, s49
	s_mov_b32 m0, s66
	ds_read_b128 v[184:187], v156 offset:16384
	ds_read_b128 v[200:203], v156 offset:17408
	ds_read_b128 v[204:207], v156 offset:18432
	ds_read_b128 v[208:211], v156 offset:19456
	ds_read_b128 v[212:215], v156 offset:20480
	ds_read_b128 v[216:219], v156 offset:21504
	ds_read_b128 v[226:229], v156 offset:22528
	ds_read_b128 v[230:233], v156 offset:23552
	global_load_lds_dwordx4 v132, s[12:13]
	s_add_i32 m0, s66, 0x2000
	s_add_u32 s66, s12, 0x40000
	s_addc_u32 s67, s13, 0
	s_add_i32 s68, s68, s49
	global_load_lds_dwordx4 v128, s[12:13]
	s_mov_b32 m0, s68
	s_mov_b64 s[100:101], s[14:15]
	global_load_lds_dwordx4 v132, s[66:67]
	s_add_i32 m0, s68, 0x2000
	s_nop 0
	global_load_lds_dwordx4 v128, s[66:67]
	s_mov_b32 m0, s56
	s_nop 0
	global_load_lds_dwordx4 v134, s[100:101]
	s_mov_b32 m0, s57
	s_nop 0
	global_load_lds_dwordx4 v130, s[100:101]
	s_waitcnt vmcnt(8)
	s_waitcnt lgkmcnt(0)
	s_barrier
	s_setprio 1
	s_waitcnt lgkmcnt(0)
	v_mfma_f32_16x16x32_bf16 v[60:63], v[140:143], v[184:187], v[60:63]
	v_mfma_f32_16x16x32_bf16 v[56:59], v[160:163], v[184:187], v[56:59]
	v_mfma_f32_16x16x32_bf16 v[44:47], v[140:143], v[204:207], v[44:47]
	v_mfma_f32_16x16x32_bf16 v[40:43], v[160:163], v[204:207], v[40:43]
	v_mfma_f32_16x16x32_bf16 v[28:31], v[140:143], v[212:215], v[28:31]
	v_mfma_f32_16x16x32_bf16 v[24:27], v[160:163], v[212:215], v[24:27]
	v_mfma_f32_16x16x32_bf16 v[12:15], v[140:143], v[226:229], v[12:15]
	v_mfma_f32_16x16x32_bf16 v[8:11], v[160:163], v[226:229], v[8:11]
	v_mfma_f32_16x16x32_bf16 v[60:63], v[144:147], v[200:203], v[60:63]
	v_mfma_f32_16x16x32_bf16 v[56:59], v[164:167], v[200:203], v[56:59]
	v_mfma_f32_16x16x32_bf16 v[44:47], v[144:147], v[208:211], v[44:47]
	v_mfma_f32_16x16x32_bf16 v[40:43], v[164:167], v[208:211], v[40:43]
	v_mfma_f32_16x16x32_bf16 v[28:31], v[144:147], v[216:219], v[28:31]
	v_mfma_f32_16x16x32_bf16 v[24:27], v[164:167], v[216:219], v[24:27]
	v_mfma_f32_16x16x32_bf16 v[12:15], v[144:147], v[230:233], v[12:15]
	v_mfma_f32_16x16x32_bf16 v[8:11], v[164:167], v[230:233], v[8:11]
	s_setprio 0
	s_setprio 1
	v_mfma_f32_16x16x32_bf16 v[52:55], v[168:171], v[184:187], v[52:55]
	v_mfma_f32_16x16x32_bf16 v[48:51], v[176:179], v[184:187], v[48:51]
	v_mfma_f32_16x16x32_bf16 v[36:39], v[168:171], v[204:207], v[36:39]
	v_mfma_f32_16x16x32_bf16 v[32:35], v[176:179], v[204:207], v[32:35]
	v_mfma_f32_16x16x32_bf16 v[20:23], v[168:171], v[212:215], v[20:23]
	v_mfma_f32_16x16x32_bf16 v[16:19], v[176:179], v[212:215], v[16:19]
	v_mfma_f32_16x16x32_bf16 v[4:7], v[168:171], v[226:229], v[4:7]
	v_mfma_f32_16x16x32_bf16 v[0:3], v[176:179], v[226:229], v[0:3]
	v_mfma_f32_16x16x32_bf16 v[52:55], v[172:175], v[200:203], v[52:55]
	v_mfma_f32_16x16x32_bf16 v[48:51], v[180:183], v[200:203], v[48:51]
	v_mfma_f32_16x16x32_bf16 v[36:39], v[172:175], v[208:211], v[36:39]
	v_mfma_f32_16x16x32_bf16 v[32:35], v[180:183], v[208:211], v[32:35]
	v_mfma_f32_16x16x32_bf16 v[20:23], v[172:175], v[216:219], v[20:23]
	v_mfma_f32_16x16x32_bf16 v[16:19], v[180:183], v[216:219], v[16:19]
	v_mfma_f32_16x16x32_bf16 v[4:7], v[172:175], v[230:233], v[4:7]
	v_mfma_f32_16x16x32_bf16 v[0:3], v[180:183], v[230:233], v[0:3]
	s_setprio 0
	s_barrier
; #define PG8_STAGE(bufoff, gbase, voff) do { _Pragma("unroll") for (int _i = 0; _i < 2; ++_i) \
;         __builtin_amdgcn_global_load_lds((const unsigned*)((const char*)(gbase) + (voff)[_i]), (PG8_LAS unsigned*)(lds + (bufoff) + ldsw + _i * 8192), 16, 0, 0); } while (0)
; #define PG8_LDA(dst, b, h) do { _Pragma("unroll") for (int m = 0; m < 4; ++m) _Pragma("unroll") for (int k = 0; k < 2; ++k) dst[m][k] = *(const PG8_LAS bf16x8*)(lds + PG8_SA(b, h) + aoff + m * 2048 + k * 1024); } while (0)
; #define PG8_LDB(dst, b, h) do { _Pragma("unroll") for (int n = 0; n < 2; ++n) _Pragma("unroll") for (int k = 0; k < 2; ++k) dst[n][k] = *(const PG8_LAS bf16x8*)(lds + PG8_SB(b, h) + boff + n * 2048 + k * 1024); } while (0)
; #define PG8_MMA(ai, bj, At, Bt) do { __builtin_amdgcn_s_setprio(1); _Pragma("unroll") for (int m = 0; m < 4; ++m) _Pragma("unroll") for (int n = 0; n < 2; ++n) _Pragma("unroll") for (int k = 0; k < 2; ++k) \
;         acc[ai][bj][m][n] = __builtin_amdgcn_mfma_f32_16x16x32_bf16(Bt[n][k], At[m][k], acc[ai][bj][m][n], 0, 0, 0); __builtin_amdgcn_s_setprio(0); } while (0)
; #define PG8_WAIT_V(n) asm volatile("s_waitcnt vmcnt(" #n ")" ::: "memory")
; #define PG8_WAIT_L(n) asm volatile("s_waitcnt lgkmcnt(" #n ")" ::: "memory")
; #define PG8_BAR __builtin_amdgcn_s_barrier()
; #define PG8_SCHED __builtin_amdgcn_sched_barrier(0)
; template <class Epi, class Sched, bool ALIGN_EPI = false, bool SP2 = false>
; __device__ __forceinline__ void gemm_phase(PG8_LAS unsigned char* lds, const Gemm g, const Sched& S, const Epi& E, int tid_in) {
;     ...
;             PG8_LDB(B0, 1, 0); PG8_LDB(B1, 1, 1); PG8_SCHED; PG8_LDA(At, 1, 0); PG8_STAGE(PG8_SA(0, 1), a2 + hstepA, voffA);
;             PG8_WAIT_V(8); PG8_WAIT_L(0); PG8_BAR; PG8_MMA(0, 0, At, B0); PG8_MMA(0, 1, At, B1); PG8_BAR; PG8_SCHED;
;             PG8_LDA(At, 1, 1); PG8_STAGE(PG8_SB(1, 0), b3, voffB); PG8_STAGE(PG8_SB(1, 1), b3 + hstep, voffB); PG8_STAGE(PG8_SA(1, 0), a3, voffA);
;             PG8_WAIT_V(8); PG8_WAIT_L(0); PG8_BAR; PG8_MMA(1, 0, At, B0); PG8_MMA(1, 1, At, B1); PG8_BAR; PG8_SCHED;
	s_add_i32 s66, 0, 0x18000
	v_add_u32_e32 v157, s66, v151
	s_add_i32 s67, 0, 0x1c000
	ds_read_b128 v[140:143], v157
	ds_read_b128 v[144:147], v157 offset:1024
	ds_read_b128 v[160:163], v157 offset:2048
	ds_read_b128 v[164:167], v157 offset:3072
	v_add_u32_e32 v157, s67, v151
	ds_read_b128 v[168:171], v157
	ds_read_b128 v[172:175], v157 offset:1024
	ds_read_b128 v[176:179], v157 offset:2048
	ds_read_b128 v[180:183], v157 offset:3072
	s_add_u32 s14, s14, 0x40000
	s_addc_u32 s15, s15, 0
	s_mov_b32 m0, s58
	ds_read_b128 v[184:187], v156 offset:32768
	ds_read_b128 v[200:203], v156 offset:33792
	ds_read_b128 v[204:207], v156 offset:34816
	ds_read_b128 v[208:211], v156 offset:35840
	ds_read_b128 v[212:215], v156 offset:36864
	ds_read_b128 v[216:219], v156 offset:37888
	ds_read_b128 v[226:229], v156 offset:38912
	ds_read_b128 v[230:233], v156 offset:39936
	global_load_lds_dwordx4 v134, s[14:15]
	s_mov_b32 m0, s59
	s_nop 0
	global_load_lds_dwordx4 v130, s[14:15]
	s_waitcnt vmcnt(8)
	s_waitcnt lgkmcnt(0)
	s_barrier
	s_setprio 1
	s_waitcnt lgkmcnt(0)
	v_mfma_f32_16x16x32_bf16 v[124:127], v[140:143], v[184:187], v[124:127]
	v_mfma_f32_16x16x32_bf16 v[120:123], v[160:163], v[184:187], v[120:123]
	v_mfma_f32_16x16x32_bf16 v[108:111], v[140:143], v[204:207], v[108:111]
	v_mfma_f32_16x16x32_bf16 v[104:107], v[160:163], v[204:207], v[104:107]
	v_mfma_f32_16x16x32_bf16 v[92:95], v[140:143], v[212:215], v[92:95]
	v_mfma_f32_16x16x32_bf16 v[88:91], v[160:163], v[212:215], v[88:91]
	v_mfma_f32_16x16x32_bf16 v[76:79], v[140:143], v[226:229], v[76:79]
	v_mfma_f32_16x16x32_bf16 v[72:75], v[160:163], v[226:229], v[72:75]
	v_mfma_f32_16x16x32_bf16 v[124:127], v[144:147], v[200:203], v[124:127]
	v_mfma_f32_16x16x32_bf16 v[120:123], v[164:167], v[200:203], v[120:123]
	v_mfma_f32_16x16x32_bf16 v[108:111], v[144:147], v[208:211], v[108:111]
	v_mfma_f32_16x16x32_bf16 v[104:107], v[164:167], v[208:211], v[104:107]
	v_mfma_f32_16x16x32_bf16 v[92:95], v[144:147], v[216:219], v[92:95]
	v_mfma_f32_16x16x32_bf16 v[88:91], v[164:167], v[216:219], v[88:91]
	v_mfma_f32_16x16x32_bf16 v[76:79], v[144:147], v[230:233], v[76:79]
	v_mfma_f32_16x16x32_bf16 v[72:75], v[164:167], v[230:233], v[72:75]
	s_setprio 0
	s_setprio 1
	v_mfma_f32_16x16x32_bf16 v[116:119], v[168:171], v[184:187], v[116:119]
	v_mfma_f32_16x16x32_bf16 v[112:115], v[176:179], v[184:187], v[112:115]
	v_mfma_f32_16x16x32_bf16 v[100:103], v[168:171], v[204:207], v[100:103]
	v_mfma_f32_16x16x32_bf16 v[96:99], v[176:179], v[204:207], v[96:99]
	v_mfma_f32_16x16x32_bf16 v[84:87], v[168:171], v[212:215], v[84:87]
	v_mfma_f32_16x16x32_bf16 v[80:83], v[176:179], v[212:215], v[80:83]
	v_mfma_f32_16x16x32_bf16 v[68:71], v[168:171], v[226:229], v[68:71]
	v_mfma_f32_16x16x32_bf16 v[64:67], v[176:179], v[226:229], v[64:67]
	v_mfma_f32_16x16x32_bf16 v[116:119], v[172:175], v[200:203], v[116:119]
	v_mfma_f32_16x16x32_bf16 v[112:115], v[180:183], v[200:203], v[112:115]
	v_mfma_f32_16x16x32_bf16 v[100:103], v[172:175], v[208:211], v[100:103]
	v_mfma_f32_16x16x32_bf16 v[96:99], v[180:183], v[208:211], v[96:99]
	v_mfma_f32_16x16x32_bf16 v[84:87], v[172:175], v[216:219], v[84:87]
	v_mfma_f32_16x16x32_bf16 v[80:83], v[180:183], v[216:219], v[80:83]
	v_mfma_f32_16x16x32_bf16 v[68:71], v[172:175], v[230:233], v[68:71]
	v_mfma_f32_16x16x32_bf16 v[64:67], v[180:183], v[230:233], v[64:67]
	s_setprio 0
	s_barrier
	s_add_i32 s14, s66, s49
	s_mov_b32 m0, s14
	ds_read_b128 v[184:187], v156 offset:49152
	ds_read_b128 v[200:203], v156 offset:50176
	ds_read_b128 v[204:207], v156 offset:51200
	ds_read_b128 v[208:211], v156 offset:52224
	ds_read_b128 v[212:215], v156 offset:53248
	ds_read_b128 v[216:219], v156 offset:54272
	ds_read_b128 v[226:229], v156 offset:55296
	ds_read_b128 v[230:233], v156 offset:56320
	s_add_u32 s12, s12, 0x80
	s_addc_u32 s13, s13, 0
	global_load_lds_dwordx4 v132, s[12:13]
	s_add_i32 m0, s14, 0x2000
	s_nop 0
	global_load_lds_dwordx4 v128, s[12:13]
	s_add_u32 s12, s12, 0x40000
	s_addc_u32 s13, s13, 0
	s_add_i32 s14, s67, s49
	s_mov_b32 m0, s14
	s_nop 0
	global_load_lds_dwordx4 v132, s[12:13]
	s_add_i32 m0, s14, 0x2000
	s_nop 0
	global_load_lds_dwordx4 v128, s[12:13]
	s_mov_b32 m0, s61
	s_nop 0
	s_add_u32 s100, s100, 0x80
	s_addc_u32 s101, s101, 0
	global_load_lds_dwordx4 v134, s[100:101]
	s_mov_b32 m0, s62
	s_nop 0
	global_load_lds_dwordx4 v130, s[100:101]
	s_waitcnt vmcnt(8)
	s_waitcnt lgkmcnt(0)
	s_barrier
	s_setprio 1
	s_waitcnt lgkmcnt(0)
	v_mfma_f32_16x16x32_bf16 v[60:63], v[140:143], v[184:187], v[60:63]
	v_mfma_f32_16x16x32_bf16 v[56:59], v[160:163], v[184:187], v[56:59]
	v_mfma_f32_16x16x32_bf16 v[44:47], v[140:143], v[204:207], v[44:47]
	v_mfma_f32_16x16x32_bf16 v[40:43], v[160:163], v[204:207], v[40:43]
	v_mfma_f32_16x16x32_bf16 v[28:31], v[140:143], v[212:215], v[28:31]
	v_mfma_f32_16x16x32_bf16 v[24:27], v[160:163], v[212:215], v[24:27]
	v_mfma_f32_16x16x32_bf16 v[12:15], v[140:143], v[226:229], v[12:15]
	v_mfma_f32_16x16x32_bf16 v[8:11], v[160:163], v[226:229], v[8:11]
	v_mfma_f32_16x16x32_bf16 v[60:63], v[144:147], v[200:203], v[60:63]
	v_mfma_f32_16x16x32_bf16 v[56:59], v[164:167], v[200:203], v[56:59]
	v_mfma_f32_16x16x32_bf16 v[44:47], v[144:147], v[208:211], v[44:47]
	v_mfma_f32_16x16x32_bf16 v[40:43], v[164:167], v[208:211], v[40:43]
	v_mfma_f32_16x16x32_bf16 v[28:31], v[144:147], v[216:219], v[28:31]
	v_mfma_f32_16x16x32_bf16 v[24:27], v[164:167], v[216:219], v[24:27]
	v_mfma_f32_16x16x32_bf16 v[12:15], v[144:147], v[230:233], v[12:15]
	v_mfma_f32_16x16x32_bf16 v[8:11], v[164:167], v[230:233], v[8:11]
	s_setprio 0
	s_setprio 1
	v_mfma_f32_16x16x32_bf16 v[52:55], v[168:171], v[184:187], v[52:55]
	v_mfma_f32_16x16x32_bf16 v[48:51], v[176:179], v[184:187], v[48:51]
	v_mfma_f32_16x16x32_bf16 v[36:39], v[168:171], v[204:207], v[36:39]
	v_mfma_f32_16x16x32_bf16 v[32:35], v[176:179], v[204:207], v[32:35]
	v_mfma_f32_16x16x32_bf16 v[20:23], v[168:171], v[212:215], v[20:23]
	v_mfma_f32_16x16x32_bf16 v[16:19], v[176:179], v[212:215], v[16:19]
	v_mfma_f32_16x16x32_bf16 v[4:7], v[168:171], v[226:229], v[4:7]
	v_mfma_f32_16x16x32_bf16 v[0:3], v[176:179], v[226:229], v[0:3]
	v_mfma_f32_16x16x32_bf16 v[52:55], v[172:175], v[200:203], v[52:55]
	v_mfma_f32_16x16x32_bf16 v[48:51], v[180:183], v[200:203], v[48:51]
	v_mfma_f32_16x16x32_bf16 v[36:39], v[172:175], v[208:211], v[36:39]
	v_mfma_f32_16x16x32_bf16 v[32:35], v[180:183], v[208:211], v[32:35]
	v_mfma_f32_16x16x32_bf16 v[20:23], v[172:175], v[216:219], v[20:23]
	v_mfma_f32_16x16x32_bf16 v[16:19], v[180:183], v[216:219], v[16:19]
	v_mfma_f32_16x16x32_bf16 v[4:7], v[172:175], v[230:233], v[4:7]
	v_mfma_f32_16x16x32_bf16 v[0:3], v[180:183], v[230:233], v[0:3]
	s_setprio 0
	s_barrier
	s_add_i32 s65, s65, 2
	s_add_u32 s51, s51, 0x100
	s_addc_u32 s64, s64, 0
	s_add_u32 s2, s2, 0x100
	s_addc_u32 s3, s3, 0
	s_cmp_gt_u32 s65, 13
	s_cbranch_scc0 .LBB0_526
	s_and_b64 vcc, exec, s[34:35]
	s_cbranch_vccz .LBB0_529
	s_barrier

; #define PG8_STAGE(bufoff, gbase, voff) do { _Pragma("unroll") for (int _i = 0; _i < 2; ++_i) \
;         __builtin_amdgcn_global_load_lds((const unsigned*)((const char*)(gbase) + (voff)[_i]), (PG8_LAS unsigned*)(lds + (bufoff) + ldsw + _i * 8192), 16, 0, 0); } while (0)
; #define PG8_LDA(dst, b, h) do { _Pragma("unroll") for (int m = 0; m < 4; ++m) _Pragma("unroll") for (int k = 0; k < 2; ++k) dst[m][k] = *(const PG8_LAS bf16x8*)(lds + PG8_SA(b, h) + aoff + m * 2048 + k * 1024); } while (0)
; #define PG8_LDB(dst, b, h) do { _Pragma("unroll") for (int n = 0; n < 2; ++n) _Pragma("unroll") for (int k = 0; k < 2; ++k) dst[n][k] = *(const PG8_LAS bf16x8*)(lds + PG8_SB(b, h) + boff + n * 2048 + k * 1024); } while (0)
; #define PG8_MMA(ai, bj, At, Bt) do { __builtin_amdgcn_s_setprio(1); _Pragma("unroll") for (int m = 0; m < 4; ++m) _Pragma("unroll") for (int n = 0; n < 2; ++n) _Pragma("unroll") for (int k = 0; k < 2; ++k) \
;         acc[ai][bj][m][n] = __builtin_amdgcn_mfma_f32_16x16x32_bf16(Bt[n][k], At[m][k], acc[ai][bj][m][n], 0, 0, 0); __builtin_amdgcn_s_setprio(0); } while (0)
; #define PG8_WAIT_V(n) asm volatile("s_waitcnt vmcnt(" #n ")" ::: "memory")
; #define PG8_WAIT_L(n) asm volatile("s_waitcnt lgkmcnt(" #n ")" ::: "memory")
; template <class Epi, class Sched, bool ALIGN_EPI = false, bool SP2 = false>
; __device__ __forceinline__ void gemm_phase(PG8_LAS unsigned char* lds, const Gemm g, const Sched& S, const Epi& E, int tid_in) {
;     ...
;             const bool last = (t == nt - 2);
;             const char* a1 = cA + (size_t)(t + 1) * kstep;
;             const char* a2 = last ? nA : cA + (size_t)(t + 2) * kstep; const char* b2 = last ? nB : cB + (size_t)(t + 2) * kstep;
;             const char* a3 = a2 + kstep; const char* b3 = b2 + kstep;
;             if (last && has_next) S.a_ready(nxt);
;             if constexpr (SP2) {
;             PG8_LDB(B0, 0, 0); PG8_LDB(B1, 0, 1); PG8_SCHED; PG8_LDA(At, 0, 0); PG8_STAGE(PG8_SA(1, 1), a1 + hstepA, voffA);
;             PG8_WAIT_V(8); PG8_WAIT_L(0); PG8_BAR; PG8_MMA(0, 0, At, B0); PG8_MMA(0, 1, At, B1); PG8_BAR; PG8_SCHED;
;             PG8_LDA(At, 0, 1); PG8_STAGE(PG8_SB(0, 0), b2, voffB); PG8_STAGE(PG8_SB(0, 1), b2 + hstep, voffB); PG8_STAGE(PG8_SA(0, 0), a2, voffA);
;             PG8_WAIT_V(8); PG8_WAIT_L(0); PG8_BAR; PG8_MMA(1, 0, At, B0); PG8_MMA(1, 1, At, B1); PG8_BAR; PG8_SCHED;
.LBB0_691:
	s_add_u32 s28, s26, 0xfffc0080
	s_addc_u32 s29, s27, -1
	s_add_i32 s57, 0, 0x10000
	s_cmp_eq_u32 s56, 12
	s_cselect_b32 s31, s15, s29
	s_cselect_b32 s30, s52, s28
	v_add_u32_e32 v147, s57, v145
	s_cselect_b32 s29, s13, s55
	s_cselect_b32 s28, s53, s54
	s_add_i32 s60, 0, 0x14000
	ds_read_b128 v[140:143], v147
	ds_read_b128 v[148:151], v147 offset:1024
	ds_read_b128 v[152:155], v147 offset:2048
	ds_read_b128 v[156:159], v147 offset:3072
	v_add_u32_e32 v147, s60, v145
	ds_read_b128 v[160:163], v147
	ds_read_b128 v[164:167], v147 offset:1024
	ds_read_b128 v[168:171], v147 offset:2048
	ds_read_b128 v[172:175], v147 offset:3072
	s_add_i32 m0, s42, 0xc000
	ds_read_b128 v[176:179], v146
	ds_read_b128 v[180:183], v146 offset:1024
	ds_read_b128 v[184:187], v146 offset:2048
	ds_read_b128 v[200:203], v146 offset:3072
	ds_read_b128 v[204:207], v146 offset:4096
	ds_read_b128 v[208:211], v146 offset:5120
	ds_read_b128 v[212:215], v146 offset:6144
	ds_read_b128 v[216:219], v146 offset:7168
	global_load_lds_dwordx4 v138, s[26:27]
	s_add_i32 m0, s42, 0xe000
	s_nop 0
	global_load_lds_dwordx4 v136, s[26:27]
	s_waitcnt vmcnt(8)
	s_waitcnt lgkmcnt(0)
	s_barrier
	s_setprio 1
	s_waitcnt lgkmcnt(0)
	v_mfma_f32_16x16x32_bf16 v[124:127], v[140:143], v[176:179], v[124:127]
	v_mfma_f32_16x16x32_bf16 v[120:123], v[152:155], v[176:179], v[120:123]
	v_mfma_f32_16x16x32_bf16 v[108:111], v[140:143], v[184:187], v[108:111]
	v_mfma_f32_16x16x32_bf16 v[104:107], v[152:155], v[184:187], v[104:107]
	v_mfma_f32_16x16x32_bf16 v[92:95], v[140:143], v[204:207], v[92:95]
	v_mfma_f32_16x16x32_bf16 v[88:91], v[152:155], v[204:207], v[88:91]
	v_mfma_f32_16x16x32_bf16 v[76:79], v[140:143], v[212:215], v[76:79]
	v_mfma_f32_16x16x32_bf16 v[72:75], v[152:155], v[212:215], v[72:75]
	v_mfma_f32_16x16x32_bf16 v[124:127], v[148:151], v[180:183], v[124:127]
	v_mfma_f32_16x16x32_bf16 v[120:123], v[156:159], v[180:183], v[120:123]
	v_mfma_f32_16x16x32_bf16 v[108:111], v[148:151], v[200:203], v[108:111]
	v_mfma_f32_16x16x32_bf16 v[104:107], v[156:159], v[200:203], v[104:107]
	v_mfma_f32_16x16x32_bf16 v[92:95], v[148:151], v[208:211], v[92:95]
	v_mfma_f32_16x16x32_bf16 v[88:91], v[156:159], v[208:211], v[88:91]
	v_mfma_f32_16x16x32_bf16 v[76:79], v[148:151], v[216:219], v[76:79]
	v_mfma_f32_16x16x32_bf16 v[72:75], v[156:159], v[216:219], v[72:75]
	s_setprio 0
	s_setprio 1
	v_mfma_f32_16x16x32_bf16 v[116:119], v[160:163], v[176:179], v[116:119]
	v_mfma_f32_16x16x32_bf16 v[112:115], v[168:171], v[176:179], v[112:115]
	v_mfma_f32_16x16x32_bf16 v[100:103], v[160:163], v[184:187], v[100:103]
	v_mfma_f32_16x16x32_bf16 v[96:99], v[168:171], v[184:187], v[96:99]
	v_mfma_f32_16x16x32_bf16 v[84:87], v[160:163], v[204:207], v[84:87]
	v_mfma_f32_16x16x32_bf16 v[80:83], v[168:171], v[204:207], v[80:83]
	v_mfma_f32_16x16x32_bf16 v[68:71], v[160:163], v[212:215], v[68:71]
	v_mfma_f32_16x16x32_bf16 v[64:67], v[168:171], v[212:215], v[64:67]
	v_mfma_f32_16x16x32_bf16 v[116:119], v[164:167], v[180:183], v[116:119]
	v_mfma_f32_16x16x32_bf16 v[112:115], v[172:175], v[180:183], v[112:115]
	v_mfma_f32_16x16x32_bf16 v[100:103], v[164:167], v[200:203], v[100:103]
	v_mfma_f32_16x16x32_bf16 v[96:99], v[172:175], v[200:203], v[96:99]
	v_mfma_f32_16x16x32_bf16 v[84:87], v[164:167], v[208:211], v[84:87]
	v_mfma_f32_16x16x32_bf16 v[80:83], v[172:175], v[208:211], v[80:83]
	v_mfma_f32_16x16x32_bf16 v[68:71], v[164:167], v[216:219], v[68:71]
	v_mfma_f32_16x16x32_bf16 v[64:67], v[172:175], v[216:219], v[64:67]
	s_setprio 0
	s_barrier
	s_add_i32 s57, s57, s41
	s_mov_b32 m0, s57
	ds_read_b128 v[176:179], v146 offset:16384
	ds_read_b128 v[180:183], v146 offset:17408
	ds_read_b128 v[184:187], v146 offset:18432
	ds_read_b128 v[200:203], v146 offset:19456
	ds_read_b128 v[204:207], v146 offset:20480
	ds_read_b128 v[208:211], v146 offset:21504
	ds_read_b128 v[212:215], v146 offset:22528
	ds_read_b128 v[216:219], v146 offset:23552
	global_load_lds_dwordx4 v132, s[28:29]
	s_add_i32 m0, s57, 0x2000
	s_add_u32 s58, s28, 0x40000
	s_addc_u32 s59, s29, 0
	s_add_i32 s57, s60, s41
	global_load_lds_dwordx4 v128, s[28:29]
	s_mov_b32 m0, s57
	s_mov_b64 s[100:101], s[30:31]
	global_load_lds_dwordx4 v132, s[58:59]
	s_add_i32 m0, s57, 0x2000
	s_nop 0
	global_load_lds_dwordx4 v128, s[58:59]
	s_mov_b32 m0, s42
	s_nop 0
	global_load_lds_dwordx4 v134, s[100:101]
	s_mov_b32 m0, s43
	s_nop 0
	global_load_lds_dwordx4 v130, s[100:101]
	s_waitcnt vmcnt(8)
	s_waitcnt lgkmcnt(0)
	s_barrier
	s_setprio 1
	s_waitcnt lgkmcnt(0)
	v_mfma_f32_16x16x32_bf16 v[60:63], v[140:143], v[176:179], v[60:63]
	v_mfma_f32_16x16x32_bf16 v[56:59], v[152:155], v[176:179], v[56:59]
	v_mfma_f32_16x16x32_bf16 v[44:47], v[140:143], v[184:187], v[44:47]
	v_mfma_f32_16x16x32_bf16 v[40:43], v[152:155], v[184:187], v[40:43]
	v_mfma_f32_16x16x32_bf16 v[28:31], v[140:143], v[204:207], v[28:31]
	v_mfma_f32_16x16x32_bf16 v[24:27], v[152:155], v[204:207], v[24:27]
	v_mfma_f32_16x16x32_bf16 v[12:15], v[140:143], v[212:215], v[12:15]
	v_mfma_f32_16x16x32_bf16 v[8:11], v[152:155], v[212:215], v[8:11]
	v_mfma_f32_16x16x32_bf16 v[60:63], v[148:151], v[180:183], v[60:63]
	v_mfma_f32_16x16x32_bf16 v[56:59], v[156:159], v[180:183], v[56:59]
	v_mfma_f32_16x16x32_bf16 v[44:47], v[148:151], v[200:203], v[44:47]
	v_mfma_f32_16x16x32_bf16 v[40:43], v[156:159], v[200:203], v[40:43]
	v_mfma_f32_16x16x32_bf16 v[28:31], v[148:151], v[208:211], v[28:31]
	v_mfma_f32_16x16x32_bf16 v[24:27], v[156:159], v[208:211], v[24:27]
	v_mfma_f32_16x16x32_bf16 v[12:15], v[148:151], v[216:219], v[12:15]
	v_mfma_f32_16x16x32_bf16 v[8:11], v[156:159], v[216:219], v[8:11]
	s_setprio 0
	s_setprio 1
	v_mfma_f32_16x16x32_bf16 v[52:55], v[160:163], v[176:179], v[52:55]
	v_mfma_f32_16x16x32_bf16 v[48:51], v[168:171], v[176:179], v[48:51]
	v_mfma_f32_16x16x32_bf16 v[36:39], v[160:163], v[184:187], v[36:39]
	v_mfma_f32_16x16x32_bf16 v[32:35], v[168:171], v[184:187], v[32:35]
	v_mfma_f32_16x16x32_bf16 v[20:23], v[160:163], v[204:207], v[20:23]
	v_mfma_f32_16x16x32_bf16 v[16:19], v[168:171], v[204:207], v[16:19]
	v_mfma_f32_16x16x32_bf16 v[4:7], v[160:163], v[212:215], v[4:7]
	v_mfma_f32_16x16x32_bf16 v[0:3], v[168:171], v[212:215], v[0:3]
	v_mfma_f32_16x16x32_bf16 v[52:55], v[164:167], v[180:183], v[52:55]
	v_mfma_f32_16x16x32_bf16 v[48:51], v[172:175], v[180:183], v[48:51]
	v_mfma_f32_16x16x32_bf16 v[36:39], v[164:167], v[200:203], v[36:39]
	v_mfma_f32_16x16x32_bf16 v[32:35], v[172:175], v[200:203], v[32:35]
	v_mfma_f32_16x16x32_bf16 v[20:23], v[164:167], v[208:211], v[20:23]
	v_mfma_f32_16x16x32_bf16 v[16:19], v[172:175], v[208:211], v[16:19]
	v_mfma_f32_16x16x32_bf16 v[4:7], v[164:167], v[216:219], v[4:7]
	v_mfma_f32_16x16x32_bf16 v[0:3], v[172:175], v[216:219], v[0:3]
	s_setprio 0
	s_barrier
; #define PG8_STAGE(bufoff, gbase, voff) do { _Pragma("unroll") for (int _i = 0; _i < 2; ++_i) \
;         __builtin_amdgcn_global_load_lds((const unsigned*)((const char*)(gbase) + (voff)[_i]), (PG8_LAS unsigned*)(lds + (bufoff) + ldsw + _i * 8192), 16, 0, 0); } while (0)
; #define PG8_LDA(dst, b, h) do { _Pragma("unroll") for (int m = 0; m < 4; ++m) _Pragma("unroll") for (int k = 0; k < 2; ++k) dst[m][k] = *(const PG8_LAS bf16x8*)(lds + PG8_SA(b, h) + aoff + m * 2048 + k * 1024); } while (0)
; #define PG8_LDB(dst, b, h) do { _Pragma("unroll") for (int n = 0; n < 2; ++n) _Pragma("unroll") for (int k = 0; k < 2; ++k) dst[n][k] = *(const PG8_LAS bf16x8*)(lds + PG8_SB(b, h) + boff + n * 2048 + k * 1024); } while (0)
; #define PG8_MMA(ai, bj, At, Bt) do { __builtin_amdgcn_s_setprio(1); _Pragma("unroll") for (int m = 0; m < 4; ++m) _Pragma("unroll") for (int n = 0; n < 2; ++n) _Pragma("unroll") for (int k = 0; k < 2; ++k) \
;         acc[ai][bj][m][n] = __builtin_amdgcn_mfma_f32_16x16x32_bf16(Bt[n][k], At[m][k], acc[ai][bj][m][n], 0, 0, 0); __builtin_amdgcn_s_setprio(0); } while (0)
; #define PG8_WAIT_V(n) asm volatile("s_waitcnt vmcnt(" #n ")" ::: "memory")
; #define PG8_WAIT_L(n) asm volatile("s_waitcnt lgkmcnt(" #n ")" ::: "memory")
; #define PG8_BAR __builtin_amdgcn_s_barrier()
; #define PG8_SCHED __builtin_amdgcn_sched_barrier(0)
; template <class Epi, class Sched, bool ALIGN_EPI = false, bool SP2 = false>
; __device__ __forceinline__ void gemm_phase(PG8_LAS unsigned char* lds, const Gemm g, const Sched& S, const Epi& E, int tid_in) {
;     ...
;             PG8_LDB(B0, 1, 0); PG8_LDB(B1, 1, 1); PG8_SCHED; PG8_LDA(At, 1, 0); PG8_STAGE(PG8_SA(0, 1), a2 + hstepA, voffA);
;             PG8_WAIT_V(8); PG8_WAIT_L(0); PG8_BAR; PG8_MMA(0, 0, At, B0); PG8_MMA(0, 1, At, B1); PG8_BAR; PG8_SCHED;
	s_add_i32 s57, 0, 0x18000
	v_add_u32_e32 v147, s57, v145
	s_add_i32 s58, 0, 0x1c000
	ds_read_b128 v[140:143], v147
	ds_read_b128 v[148:151], v147 offset:1024
	ds_read_b128 v[152:155], v147 offset:2048
	ds_read_b128 v[156:159], v147 offset:3072
	v_add_u32_e32 v147, s58, v145
	ds_read_b128 v[160:163], v147
	ds_read_b128 v[164:167], v147 offset:1024
	ds_read_b128 v[168:171], v147 offset:2048
	ds_read_b128 v[172:175], v147 offset:3072
	s_add_u32 s30, s30, 0x40000
	s_addc_u32 s31, s31, 0
	s_mov_b32 m0, s44
	ds_read_b128 v[176:179], v146 offset:32768
	ds_read_b128 v[180:183], v146 offset:33792
	ds_read_b128 v[184:187], v146 offset:34816
	ds_read_b128 v[200:203], v146 offset:35840
	ds_read_b128 v[204:207], v146 offset:36864
	ds_read_b128 v[208:211], v146 offset:37888
	ds_read_b128 v[212:215], v146 offset:38912
	ds_read_b128 v[216:219], v146 offset:39936
	global_load_lds_dwordx4 v134, s[30:31]
	s_mov_b32 m0, s45
	s_nop 0
	global_load_lds_dwordx4 v130, s[30:31]
	s_waitcnt vmcnt(8)
	s_waitcnt lgkmcnt(0)
	s_barrier
	s_setprio 1
	s_waitcnt lgkmcnt(0)
	v_mfma_f32_16x16x32_bf16 v[124:127], v[140:143], v[176:179], v[124:127]
	v_mfma_f32_16x16x32_bf16 v[120:123], v[152:155], v[176:179], v[120:123]
	v_mfma_f32_16x16x32_bf16 v[108:111], v[140:143], v[184:187], v[108:111]
	v_mfma_f32_16x16x32_bf16 v[104:107], v[152:155], v[184:187], v[104:107]
	v_mfma_f32_16x16x32_bf16 v[92:95], v[140:143], v[204:207], v[92:95]
	v_mfma_f32_16x16x32_bf16 v[88:91], v[152:155], v[204:207], v[88:91]
	v_mfma_f32_16x16x32_bf16 v[76:79], v[140:143], v[212:215], v[76:79]
	v_mfma_f32_16x16x32_bf16 v[72:75], v[152:155], v[212:215], v[72:75]
	v_mfma_f32_16x16x32_bf16 v[124:127], v[148:151], v[180:183], v[124:127]
	v_mfma_f32_16x16x32_bf16 v[120:123], v[156:159], v[180:183], v[120:123]
	v_mfma_f32_16x16x32_bf16 v[108:111], v[148:151], v[200:203], v[108:111]
	v_mfma_f32_16x16x32_bf16 v[104:107], v[156:159], v[200:203], v[104:107]
	v_mfma_f32_16x16x32_bf16 v[92:95], v[148:151], v[208:211], v[92:95]
	v_mfma_f32_16x16x32_bf16 v[88:91], v[156:159], v[208:211], v[88:91]
	v_mfma_f32_16x16x32_bf16 v[76:79], v[148:151], v[216:219], v[76:79]
	v_mfma_f32_16x16x32_bf16 v[72:75], v[156:159], v[216:219], v[72:75]
	s_setprio 0
	s_setprio 1
	v_mfma_f32_16x16x32_bf16 v[116:119], v[160:163], v[176:179], v[116:119]
	v_mfma_f32_16x16x32_bf16 v[112:115], v[168:171], v[176:179], v[112:115]
	v_mfma_f32_16x16x32_bf16 v[100:103], v[160:163], v[184:187], v[100:103]
	v_mfma_f32_16x16x32_bf16 v[96:99], v[168:171], v[184:187], v[96:99]
	v_mfma_f32_16x16x32_bf16 v[84:87], v[160:163], v[204:207], v[84:87]
	v_mfma_f32_16x16x32_bf16 v[80:83], v[168:171], v[204:207], v[80:83]
	v_mfma_f32_16x16x32_bf16 v[68:71], v[160:163], v[212:215], v[68:71]
	v_mfma_f32_16x16x32_bf16 v[64:67], v[168:171], v[212:215], v[64:67]
	v_mfma_f32_16x16x32_bf16 v[116:119], v[164:167], v[180:183], v[116:119]
	v_mfma_f32_16x16x32_bf16 v[112:115], v[172:175], v[180:183], v[112:115]
	v_mfma_f32_16x16x32_bf16 v[100:103], v[164:167], v[200:203], v[100:103]
	v_mfma_f32_16x16x32_bf16 v[96:99], v[172:175], v[200:203], v[96:99]
	v_mfma_f32_16x16x32_bf16 v[84:87], v[164:167], v[208:211], v[84:87]
	v_mfma_f32_16x16x32_bf16 v[80:83], v[172:175], v[208:211], v[80:83]
	v_mfma_f32_16x16x32_bf16 v[68:71], v[164:167], v[216:219], v[68:71]
	v_mfma_f32_16x16x32_bf16 v[64:67], v[172:175], v[216:219], v[64:67]
	s_setprio 0
	s_barrier
; #define PG8_STAGE(bufoff, gbase, voff) do { _Pragma("unroll") for (int _i = 0; _i < 2; ++_i) \
;         __builtin_amdgcn_global_load_lds((const unsigned*)((const char*)(gbase) + (voff)[_i]), (PG8_LAS unsigned*)(lds + (bufoff) + ldsw + _i * 8192), 16, 0, 0); } while (0)
; #define PG8_LDA(dst, b, h) do { _Pragma("unroll") for (int m = 0; m < 4; ++m) _Pragma("unroll") for (int k = 0; k < 2; ++k) dst[m][k] = *(const PG8_LAS bf16x8*)(lds + PG8_SA(b, h) + aoff + m * 2048 + k * 1024); } while (0)
; #define PG8_MMA(ai, bj, At, Bt) do { __builtin_amdgcn_s_setprio(1); _Pragma("unroll") for (int m = 0; m < 4; ++m) _Pragma("unroll") for (int n = 0; n < 2; ++n) _Pragma("unroll") for (int k = 0; k < 2; ++k) \
;         acc[ai][bj][m][n] = __builtin_amdgcn_mfma_f32_16x16x32_bf16(Bt[n][k], At[m][k], acc[ai][bj][m][n], 0, 0, 0); __builtin_amdgcn_s_setprio(0); } while (0)
; #define PG8_WAIT_V(n) asm volatile("s_waitcnt vmcnt(" #n ")" ::: "memory")
; #define PG8_WAIT_L(n) asm volatile("s_waitcnt lgkmcnt(" #n ")" ::: "memory")
; #define PG8_BAR __builtin_amdgcn_s_barrier()
; #define PG8_SCHED __builtin_amdgcn_sched_barrier(0)
; template <class Epi, class Sched, bool ALIGN_EPI = false, bool SP2 = false>
; __device__ __forceinline__ void gemm_phase(PG8_LAS unsigned char* lds, const Gemm g, const Sched& S, const Epi& E, int tid_in) {
;     ...
;             PG8_LDA(At, 1, 1); PG8_STAGE(PG8_SB(1, 0), b3, voffB); PG8_STAGE(PG8_SB(1, 1), b3 + hstep, voffB); PG8_STAGE(PG8_SA(1, 0), a3, voffA);
;             PG8_WAIT_V(8); PG8_WAIT_L(0); PG8_BAR; PG8_MMA(1, 0, At, B0); PG8_MMA(1, 1, At, B1); PG8_BAR; PG8_SCHED;
	s_add_i32 s30, s57, s41
	s_mov_b32 m0, s30
	ds_read_b128 v[176:179], v146 offset:49152
	ds_read_b128 v[180:183], v146 offset:50176
	ds_read_b128 v[184:187], v146 offset:51200
	ds_read_b128 v[200:203], v146 offset:52224
	ds_read_b128 v[204:207], v146 offset:53248
	ds_read_b128 v[208:211], v146 offset:54272
	ds_read_b128 v[212:215], v146 offset:55296
	ds_read_b128 v[216:219], v146 offset:56320
	s_add_u32 s28, s28, 0x80
	s_addc_u32 s29, s29, 0
	global_load_lds_dwordx4 v132, s[28:29]
	s_add_i32 m0, s30, 0x2000
	s_nop 0
	global_load_lds_dwordx4 v128, s[28:29]
	s_add_u32 s28, s28, 0x40000
	s_addc_u32 s29, s29, 0
	s_add_i32 s30, s58, s41
	s_mov_b32 m0, s30
	s_nop 0
	global_load_lds_dwordx4 v132, s[28:29]
	s_add_i32 m0, s30, 0x2000
	s_nop 0
	global_load_lds_dwordx4 v128, s[28:29]
	s_mov_b32 m0, s46
	s_nop 0
	s_add_u32 s100, s100, 0x80
	s_addc_u32 s101, s101, 0
	global_load_lds_dwordx4 v134, s[100:101]
	s_mov_b32 m0, s47
	s_nop 0
	global_load_lds_dwordx4 v130, s[100:101]
	s_waitcnt vmcnt(8)
	s_waitcnt lgkmcnt(0)
	s_barrier
	s_setprio 1
	s_waitcnt lgkmcnt(0)
	v_mfma_f32_16x16x32_bf16 v[60:63], v[140:143], v[176:179], v[60:63]
	v_mfma_f32_16x16x32_bf16 v[56:59], v[152:155], v[176:179], v[56:59]
	v_mfma_f32_16x16x32_bf16 v[44:47], v[140:143], v[184:187], v[44:47]
	v_mfma_f32_16x16x32_bf16 v[40:43], v[152:155], v[184:187], v[40:43]
	v_mfma_f32_16x16x32_bf16 v[28:31], v[140:143], v[204:207], v[28:31]
	v_mfma_f32_16x16x32_bf16 v[24:27], v[152:155], v[204:207], v[24:27]
	v_mfma_f32_16x16x32_bf16 v[12:15], v[140:143], v[212:215], v[12:15]
	v_mfma_f32_16x16x32_bf16 v[8:11], v[152:155], v[212:215], v[8:11]
	v_mfma_f32_16x16x32_bf16 v[60:63], v[148:151], v[180:183], v[60:63]
	v_mfma_f32_16x16x32_bf16 v[56:59], v[156:159], v[180:183], v[56:59]
	v_mfma_f32_16x16x32_bf16 v[44:47], v[148:151], v[200:203], v[44:47]
	v_mfma_f32_16x16x32_bf16 v[40:43], v[156:159], v[200:203], v[40:43]
	v_mfma_f32_16x16x32_bf16 v[28:31], v[148:151], v[208:211], v[28:31]
	v_mfma_f32_16x16x32_bf16 v[24:27], v[156:159], v[208:211], v[24:27]
	v_mfma_f32_16x16x32_bf16 v[12:15], v[148:151], v[216:219], v[12:15]
	v_mfma_f32_16x16x32_bf16 v[8:11], v[156:159], v[216:219], v[8:11]
	s_setprio 0
	s_setprio 1
	v_mfma_f32_16x16x32_bf16 v[52:55], v[160:163], v[176:179], v[52:55]
	v_mfma_f32_16x16x32_bf16 v[48:51], v[168:171], v[176:179], v[48:51]
	v_mfma_f32_16x16x32_bf16 v[36:39], v[160:163], v[184:187], v[36:39]
	v_mfma_f32_16x16x32_bf16 v[32:35], v[168:171], v[184:187], v[32:35]
	v_mfma_f32_16x16x32_bf16 v[20:23], v[160:163], v[204:207], v[20:23]
	v_mfma_f32_16x16x32_bf16 v[16:19], v[168:171], v[204:207], v[16:19]
	v_mfma_f32_16x16x32_bf16 v[4:7], v[160:163], v[212:215], v[4:7]
	v_mfma_f32_16x16x32_bf16 v[0:3], v[168:171], v[212:215], v[0:3]
	v_mfma_f32_16x16x32_bf16 v[52:55], v[164:167], v[180:183], v[52:55]
	v_mfma_f32_16x16x32_bf16 v[48:51], v[172:175], v[180:183], v[48:51]
	v_mfma_f32_16x16x32_bf16 v[36:39], v[164:167], v[200:203], v[36:39]
	v_mfma_f32_16x16x32_bf16 v[32:35], v[172:175], v[200:203], v[32:35]
	v_mfma_f32_16x16x32_bf16 v[20:23], v[164:167], v[208:211], v[20:23]
	v_mfma_f32_16x16x32_bf16 v[16:19], v[172:175], v[208:211], v[16:19]
	v_mfma_f32_16x16x32_bf16 v[4:7], v[164:167], v[216:219], v[4:7]
	v_mfma_f32_16x16x32_bf16 v[0:3], v[172:175], v[216:219], v[0:3]
	s_setprio 0
	s_barrier
	s_add_i32 s56, s56, 2
	s_add_u32 s54, s54, 0x100
	s_addc_u32 s55, s55, 0
	s_add_u32 s26, s26, 0x100
	s_addc_u32 s27, s27, 0
	s_cmp_gt_u32 s56, 13
	s_cbranch_scc0 .LBB0_691
	v_readlane_b32 s56, v255, 17
	s_and_b64 vcc, exec, s[10:11]
	s_mov_b64 s[30:31], 0x10000600
	v_readlane_b32 s57, v255, 18
	v_readlane_b32 s58, v255, 19
	v_readlane_b32 s59, v255, 20
	s_cbranch_vccz .LBB0_694
	s_barrier

; #define PG8_STAGE(bufoff, gbase, voff) do { _Pragma("unroll") for (int _i = 0; _i < 2; ++_i) \
;         __builtin_amdgcn_global_load_lds((const unsigned*)((const char*)(gbase) + (voff)[_i]), (PG8_LAS unsigned*)(lds + (bufoff) + ldsw + _i * 8192), 16, 0, 0); } while (0)
; #define PG8_LDA(dst, b, h) do { _Pragma("unroll") for (int m = 0; m < 4; ++m) _Pragma("unroll") for (int k = 0; k < 2; ++k) dst[m][k] = *(const PG8_LAS bf16x8*)(lds + PG8_SA(b, h) + aoff + m * 2048 + k * 1024); } while (0)
; #define PG8_LDB(dst, b, h) do { _Pragma("unroll") for (int n = 0; n < 2; ++n) _Pragma("unroll") for (int k = 0; k < 2; ++k) dst[n][k] = *(const PG8_LAS bf16x8*)(lds + PG8_SB(b, h) + boff + n * 2048 + k * 1024); } while (0)
; #define PG8_MMA(ai, bj, At, Bt) do { __builtin_amdgcn_s_setprio(1); _Pragma("unroll") for (int m = 0; m < 4; ++m) _Pragma("unroll") for (int n = 0; n < 2; ++n) _Pragma("unroll") for (int k = 0; k < 2; ++k) \
;         acc[ai][bj][m][n] = __builtin_amdgcn_mfma_f32_16x16x32_bf16(Bt[n][k], At[m][k], acc[ai][bj][m][n], 0, 0, 0); __builtin_amdgcn_s_setprio(0); } while (0)
; #define PG8_WAIT_V(n) asm volatile("s_waitcnt vmcnt(" #n ")" ::: "memory")
; #define PG8_WAIT_L(n) asm volatile("s_waitcnt lgkmcnt(" #n ")" ::: "memory")
; #define PG8_BAR __builtin_amdgcn_s_barrier()
; #define PG8_SCHED __builtin_amdgcn_sched_barrier(0)
; template <class Epi, class Sched, bool ALIGN_EPI = false, bool SP2 = false>
; __device__ __forceinline__ void gemm_phase(PG8_LAS unsigned char* lds, const Gemm g, const Sched& S, const Epi& E, int tid_in) {
;     ...
;             const bool last = (t == nt - 2);
;             const char* a1 = cA + (size_t)(t + 1) * kstep;
;             const char* a2 = last ? nA : cA + (size_t)(t + 2) * kstep; const char* b2 = last ? nB : cB + (size_t)(t + 2) * kstep;
;             const char* a3 = a2 + kstep; const char* b3 = b2 + kstep;
;             if (last && has_next) S.a_ready(nxt);
;             if constexpr (SP2) {
;             PG8_LDB(B0, 0, 0); PG8_LDB(B1, 0, 1); PG8_SCHED; PG8_LDA(At, 0, 0); PG8_STAGE(PG8_SA(1, 1), a1 + hstepA, voffA);
;             PG8_WAIT_V(8); PG8_WAIT_L(0); PG8_BAR; PG8_MMA(0, 0, At, B0); PG8_MMA(0, 1, At, B1); PG8_BAR; PG8_SCHED;
;             PG8_LDA(At, 0, 1); PG8_STAGE(PG8_SB(0, 0), b2, voffB); PG8_STAGE(PG8_SB(0, 1), b2 + hstep, voffB); PG8_STAGE(PG8_SA(0, 0), a2, voffA);
.LBB0_782:
	s_add_u32 s26, s24, 0xfffc0080
	s_addc_u32 s27, s25, -1
	s_add_i32 s54, 0, 0x10000
	s_cmp_eq_u32 s53, 28
	s_cselect_b32 s29, s15, s27
	s_cselect_b32 s28, s49, s26
	s_cselect_b32 s27, s13, s52
	s_cselect_b32 s26, s50, s51
	s_add_i32 s56, 0, 0x14000
	v_add_u32_e32 v158, s54, v156
	v_add_u32_e32 v174, s56, v156
	ds_read_b128 v[96:99], v158
	ds_read_b128 v[100:103], v158 offset:1024
	ds_read_b128 v[150:153], v158 offset:2048
	ds_read_b128 v[158:161], v158 offset:3072
	ds_read_b128 v[162:165], v174
	ds_read_b128 v[166:169], v174 offset:1024
	ds_read_b128 v[170:173], v174 offset:2048
	ds_read_b128 v[174:177], v174 offset:3072
	s_add_i32 m0, s38, 0xc000
	ds_read_b128 v[178:181], v157
	ds_read_b128 v[182:185], v157 offset:1024
	ds_read_b128 v[186:189], v157 offset:2048
	ds_read_b128 v[200:203], v157 offset:3072
	ds_read_b128 v[204:207], v157 offset:4096
	ds_read_b128 v[208:211], v157 offset:5120
	ds_read_b128 v[212:215], v157 offset:6144
	ds_read_b128 v[216:219], v157 offset:7168
	global_load_lds_dwordx4 v148, s[24:25]
	s_add_i32 m0, s38, 0xe000
	s_nop 0
	global_load_lds_dwordx4 v146, s[24:25]
	s_waitcnt vmcnt(8)
	s_waitcnt lgkmcnt(0)
	s_barrier
	s_setprio 1
	s_waitcnt lgkmcnt(0)
	v_mfma_f32_16x16x32_bf16 v[132:135], v[96:99], v[178:181], v[132:135]
	v_mfma_f32_16x16x32_bf16 v[128:131], v[150:153], v[178:181], v[128:131]
	v_mfma_f32_16x16x32_bf16 v[124:127], v[96:99], v[186:189], v[124:127]
	v_mfma_f32_16x16x32_bf16 v[120:123], v[150:153], v[186:189], v[120:123]
	v_mfma_f32_16x16x32_bf16 v[116:119], v[96:99], v[204:207], v[116:119]
	v_mfma_f32_16x16x32_bf16 v[112:115], v[150:153], v[204:207], v[112:115]
	v_mfma_f32_16x16x32_bf16 v[108:111], v[96:99], v[212:215], v[108:111]
	v_mfma_f32_16x16x32_bf16 v[104:107], v[150:153], v[212:215], v[104:107]
	v_mfma_f32_16x16x32_bf16 v[132:135], v[100:103], v[182:185], v[132:135]
	v_mfma_f32_16x16x32_bf16 v[128:131], v[158:161], v[182:185], v[128:131]
	v_mfma_f32_16x16x32_bf16 v[124:127], v[100:103], v[200:203], v[124:127]
	v_mfma_f32_16x16x32_bf16 v[120:123], v[158:161], v[200:203], v[120:123]
	v_mfma_f32_16x16x32_bf16 v[116:119], v[100:103], v[208:211], v[116:119]
	v_mfma_f32_16x16x32_bf16 v[112:115], v[158:161], v[208:211], v[112:115]
	v_mfma_f32_16x16x32_bf16 v[108:111], v[100:103], v[216:219], v[108:111]
	v_mfma_f32_16x16x32_bf16 v[104:107], v[158:161], v[216:219], v[104:107]
	s_setprio 0
	s_setprio 1
	v_mfma_f32_16x16x32_bf16 v[60:63], v[162:165], v[178:181], v[60:63]
	v_mfma_f32_16x16x32_bf16 v[56:59], v[170:173], v[178:181], v[56:59]
	v_mfma_f32_16x16x32_bf16 v[52:55], v[162:165], v[186:189], v[52:55]
	v_mfma_f32_16x16x32_bf16 v[48:51], v[170:173], v[186:189], v[48:51]
	v_mfma_f32_16x16x32_bf16 v[44:47], v[162:165], v[204:207], v[44:47]
	v_mfma_f32_16x16x32_bf16 v[40:43], v[170:173], v[204:207], v[40:43]
	v_mfma_f32_16x16x32_bf16 v[36:39], v[162:165], v[212:215], v[36:39]
	v_mfma_f32_16x16x32_bf16 v[32:35], v[170:173], v[212:215], v[32:35]
	v_mfma_f32_16x16x32_bf16 v[60:63], v[166:169], v[182:185], v[60:63]
	v_mfma_f32_16x16x32_bf16 v[56:59], v[174:177], v[182:185], v[56:59]
	v_mfma_f32_16x16x32_bf16 v[52:55], v[166:169], v[200:203], v[52:55]
	v_mfma_f32_16x16x32_bf16 v[48:51], v[174:177], v[200:203], v[48:51]
	v_mfma_f32_16x16x32_bf16 v[44:47], v[166:169], v[208:211], v[44:47]
	v_mfma_f32_16x16x32_bf16 v[40:43], v[174:177], v[208:211], v[40:43]
	v_mfma_f32_16x16x32_bf16 v[36:39], v[166:169], v[216:219], v[36:39]
	v_mfma_f32_16x16x32_bf16 v[32:35], v[174:177], v[216:219], v[32:35]
	s_setprio 0
	s_barrier
	s_add_i32 s54, s54, s35
	s_mov_b64 s[100:101], s[26:27]
	s_mov_b32 m0, s54
	ds_read_b128 v[178:181], v157 offset:16384
	ds_read_b128 v[182:185], v157 offset:17408
	ds_read_b128 v[186:189], v157 offset:18432
	ds_read_b128 v[200:203], v157 offset:19456
	ds_read_b128 v[204:207], v157 offset:20480
	ds_read_b128 v[208:211], v157 offset:21504
	ds_read_b128 v[212:215], v157 offset:22528
	ds_read_b128 v[216:219], v157 offset:23552
	global_load_lds_dwordx4 v190, s[100:101]
	s_add_i32 m0, s54, 0x2000
	s_add_u32 s54, s26, 0x80000
	s_addc_u32 s55, s27, 0
	s_add_i32 s56, s56, s35
	global_load_lds_dwordx4 v136, s[100:101]
	s_mov_b32 m0, s56
	v_lshl_add_u64 v[232:233], s[28:29], 0, v[138:139]
	global_load_lds_dwordx4 v190, s[54:55]
	s_add_i32 m0, s56, 0x2000
	s_nop 0
	global_load_lds_dwordx4 v136, s[54:55]
	v_lshl_add_u64 v[230:231], s[28:29], 0, v[140:141]
	s_mov_b32 m0, s38
	s_nop 0
	global_load_lds_dwordx4 v[230:231], off
	s_mov_b32 m0, s40
	s_nop 0
	global_load_lds_dwordx4 v[232:233], off
	s_waitcnt vmcnt(8)
	s_waitcnt lgkmcnt(0)
	s_barrier
; #define PG8_STAGE(bufoff, gbase, voff) do { _Pragma("unroll") for (int _i = 0; _i < 2; ++_i) \
;         __builtin_amdgcn_global_load_lds((const unsigned*)((const char*)(gbase) + (voff)[_i]), (PG8_LAS unsigned*)(lds + (bufoff) + ldsw + _i * 8192), 16, 0, 0); } while (0)
; #define PG8_LDA(dst, b, h) do { _Pragma("unroll") for (int m = 0; m < 4; ++m) _Pragma("unroll") for (int k = 0; k < 2; ++k) dst[m][k] = *(const PG8_LAS bf16x8*)(lds + PG8_SA(b, h) + aoff + m * 2048 + k * 1024); } while (0)
; #define PG8_LDB(dst, b, h) do { _Pragma("unroll") for (int n = 0; n < 2; ++n) _Pragma("unroll") for (int k = 0; k < 2; ++k) dst[n][k] = *(const PG8_LAS bf16x8*)(lds + PG8_SB(b, h) + boff + n * 2048 + k * 1024); } while (0)
; #define PG8_MMA(ai, bj, At, Bt) do { __builtin_amdgcn_s_setprio(1); _Pragma("unroll") for (int m = 0; m < 4; ++m) _Pragma("unroll") for (int n = 0; n < 2; ++n) _Pragma("unroll") for (int k = 0; k < 2; ++k) \
;         acc[ai][bj][m][n] = __builtin_amdgcn_mfma_f32_16x16x32_bf16(Bt[n][k], At[m][k], acc[ai][bj][m][n], 0, 0, 0); __builtin_amdgcn_s_setprio(0); } while (0)
; #define PG8_WAIT_V(n) asm volatile("s_waitcnt vmcnt(" #n ")" ::: "memory")
; #define PG8_WAIT_L(n) asm volatile("s_waitcnt lgkmcnt(" #n ")" ::: "memory")
; #define PG8_BAR __builtin_amdgcn_s_barrier()
; #define PG8_SCHED __builtin_amdgcn_sched_barrier(0)
; template <class Epi, class Sched, bool ALIGN_EPI = false, bool SP2 = false>
; __device__ __forceinline__ void gemm_phase(PG8_LAS unsigned char* lds, const Gemm g, const Sched& S, const Epi& E, int tid_in) {
;     ...
;             PG8_WAIT_V(8); PG8_WAIT_L(0); PG8_BAR; PG8_MMA(1, 0, At, B0); PG8_MMA(1, 1, At, B1); PG8_BAR; PG8_SCHED;
;             PG8_LDB(B0, 1, 0); PG8_LDB(B1, 1, 1); PG8_SCHED; PG8_LDA(At, 1, 0); PG8_STAGE(PG8_SA(0, 1), a2 + hstepA, voffA);
;             PG8_WAIT_V(8); PG8_WAIT_L(0); PG8_BAR; PG8_MMA(0, 0, At, B0); PG8_MMA(0, 1, At, B1); PG8_BAR; PG8_SCHED;
	s_setprio 1
	s_waitcnt lgkmcnt(0)
	v_mfma_f32_16x16x32_bf16 v[92:95], v[96:99], v[178:181], v[92:95]
	v_mfma_f32_16x16x32_bf16 v[88:91], v[150:153], v[178:181], v[88:91]
	v_mfma_f32_16x16x32_bf16 v[84:87], v[96:99], v[186:189], v[84:87]
	v_mfma_f32_16x16x32_bf16 v[80:83], v[150:153], v[186:189], v[80:83]
	v_mfma_f32_16x16x32_bf16 v[76:79], v[96:99], v[204:207], v[76:79]
	v_mfma_f32_16x16x32_bf16 v[72:75], v[150:153], v[204:207], v[72:75]
	v_mfma_f32_16x16x32_bf16 v[68:71], v[96:99], v[212:215], v[68:71]
	v_mfma_f32_16x16x32_bf16 v[64:67], v[150:153], v[212:215], v[64:67]
	v_mfma_f32_16x16x32_bf16 v[92:95], v[100:103], v[182:185], v[92:95]
	v_mfma_f32_16x16x32_bf16 v[88:91], v[158:161], v[182:185], v[88:91]
	v_mfma_f32_16x16x32_bf16 v[84:87], v[100:103], v[200:203], v[84:87]
	v_mfma_f32_16x16x32_bf16 v[80:83], v[158:161], v[200:203], v[80:83]
	v_mfma_f32_16x16x32_bf16 v[76:79], v[100:103], v[208:211], v[76:79]
	v_mfma_f32_16x16x32_bf16 v[72:75], v[158:161], v[208:211], v[72:75]
	v_mfma_f32_16x16x32_bf16 v[68:71], v[100:103], v[216:219], v[68:71]
	v_mfma_f32_16x16x32_bf16 v[64:67], v[158:161], v[216:219], v[64:67]
	s_setprio 0
	s_setprio 1
	v_mfma_f32_16x16x32_bf16 v[28:31], v[162:165], v[178:181], v[28:31]
	v_mfma_f32_16x16x32_bf16 v[24:27], v[170:173], v[178:181], v[24:27]
	v_mfma_f32_16x16x32_bf16 v[20:23], v[162:165], v[186:189], v[20:23]
	v_mfma_f32_16x16x32_bf16 v[16:19], v[170:173], v[186:189], v[16:19]
	v_mfma_f32_16x16x32_bf16 v[12:15], v[162:165], v[204:207], v[12:15]
	v_mfma_f32_16x16x32_bf16 v[8:11], v[170:173], v[204:207], v[8:11]
	v_mfma_f32_16x16x32_bf16 v[4:7], v[162:165], v[212:215], v[4:7]
	v_mfma_f32_16x16x32_bf16 v[0:3], v[170:173], v[212:215], v[0:3]
	v_mfma_f32_16x16x32_bf16 v[28:31], v[166:169], v[182:185], v[28:31]
	v_mfma_f32_16x16x32_bf16 v[24:27], v[174:177], v[182:185], v[24:27]
	v_mfma_f32_16x16x32_bf16 v[20:23], v[166:169], v[200:203], v[20:23]
	v_mfma_f32_16x16x32_bf16 v[16:19], v[174:177], v[200:203], v[16:19]
	v_mfma_f32_16x16x32_bf16 v[12:15], v[166:169], v[208:211], v[12:15]
	v_mfma_f32_16x16x32_bf16 v[8:11], v[174:177], v[208:211], v[8:11]
	v_mfma_f32_16x16x32_bf16 v[4:7], v[166:169], v[216:219], v[4:7]
	v_mfma_f32_16x16x32_bf16 v[0:3], v[174:177], v[216:219], v[0:3]
	s_setprio 0
	s_barrier
	s_add_i32 s54, 0, 0x18000
	s_add_i32 s55, 0, 0x1c000
	v_add_u32_e32 v158, s54, v156
	v_add_u32_e32 v174, s55, v156
	ds_read_b128 v[96:99], v158
	ds_read_b128 v[100:103], v158 offset:1024
	ds_read_b128 v[150:153], v158 offset:2048
	ds_read_b128 v[158:161], v158 offset:3072
	ds_read_b128 v[162:165], v174
	ds_read_b128 v[166:169], v174 offset:1024
	ds_read_b128 v[170:173], v174 offset:2048
	ds_read_b128 v[174:177], v174 offset:3072
	s_add_u32 s28, s28, 0x40000
	s_addc_u32 s29, s29, 0
	s_mov_b32 m0, s41
	ds_read_b128 v[178:181], v157 offset:32768
	ds_read_b128 v[182:185], v157 offset:33792
	ds_read_b128 v[186:189], v157 offset:34816
	ds_read_b128 v[200:203], v157 offset:35840
	ds_read_b128 v[204:207], v157 offset:36864
	ds_read_b128 v[208:211], v157 offset:37888
	ds_read_b128 v[212:215], v157 offset:38912
	ds_read_b128 v[216:219], v157 offset:39936
	global_load_lds_dwordx4 v140, s[28:29]
	s_mov_b32 m0, s42
	s_nop 0
	global_load_lds_dwordx4 v138, s[28:29]
	s_waitcnt vmcnt(8)
	s_waitcnt lgkmcnt(0)
	s_barrier
	s_setprio 1
	s_waitcnt lgkmcnt(0)
	v_mfma_f32_16x16x32_bf16 v[132:135], v[96:99], v[178:181], v[132:135]
	v_mfma_f32_16x16x32_bf16 v[128:131], v[150:153], v[178:181], v[128:131]
	v_mfma_f32_16x16x32_bf16 v[124:127], v[96:99], v[186:189], v[124:127]
	v_mfma_f32_16x16x32_bf16 v[120:123], v[150:153], v[186:189], v[120:123]
	v_mfma_f32_16x16x32_bf16 v[116:119], v[96:99], v[204:207], v[116:119]
	v_mfma_f32_16x16x32_bf16 v[112:115], v[150:153], v[204:207], v[112:115]
	v_mfma_f32_16x16x32_bf16 v[108:111], v[96:99], v[212:215], v[108:111]
	v_mfma_f32_16x16x32_bf16 v[104:107], v[150:153], v[212:215], v[104:107]
	v_mfma_f32_16x16x32_bf16 v[132:135], v[100:103], v[182:185], v[132:135]
	v_mfma_f32_16x16x32_bf16 v[128:131], v[158:161], v[182:185], v[128:131]
	v_mfma_f32_16x16x32_bf16 v[124:127], v[100:103], v[200:203], v[124:127]
	v_mfma_f32_16x16x32_bf16 v[120:123], v[158:161], v[200:203], v[120:123]
	v_mfma_f32_16x16x32_bf16 v[116:119], v[100:103], v[208:211], v[116:119]
	v_mfma_f32_16x16x32_bf16 v[112:115], v[158:161], v[208:211], v[112:115]
	v_mfma_f32_16x16x32_bf16 v[108:111], v[100:103], v[216:219], v[108:111]
	v_mfma_f32_16x16x32_bf16 v[104:107], v[158:161], v[216:219], v[104:107]
	s_setprio 0
	s_setprio 1
	v_mfma_f32_16x16x32_bf16 v[60:63], v[162:165], v[178:181], v[60:63]
	v_mfma_f32_16x16x32_bf16 v[56:59], v[170:173], v[178:181], v[56:59]
	v_mfma_f32_16x16x32_bf16 v[52:55], v[162:165], v[186:189], v[52:55]
	v_mfma_f32_16x16x32_bf16 v[48:51], v[170:173], v[186:189], v[48:51]
	v_mfma_f32_16x16x32_bf16 v[44:47], v[162:165], v[204:207], v[44:47]
	v_mfma_f32_16x16x32_bf16 v[40:43], v[170:173], v[204:207], v[40:43]
	v_mfma_f32_16x16x32_bf16 v[36:39], v[162:165], v[212:215], v[36:39]
	v_mfma_f32_16x16x32_bf16 v[32:35], v[170:173], v[212:215], v[32:35]
	v_mfma_f32_16x16x32_bf16 v[60:63], v[166:169], v[182:185], v[60:63]
	v_mfma_f32_16x16x32_bf16 v[56:59], v[174:177], v[182:185], v[56:59]
	v_mfma_f32_16x16x32_bf16 v[52:55], v[166:169], v[200:203], v[52:55]
	v_mfma_f32_16x16x32_bf16 v[48:51], v[174:177], v[200:203], v[48:51]
	v_mfma_f32_16x16x32_bf16 v[44:47], v[166:169], v[208:211], v[44:47]
	v_mfma_f32_16x16x32_bf16 v[40:43], v[174:177], v[208:211], v[40:43]
	v_mfma_f32_16x16x32_bf16 v[36:39], v[166:169], v[216:219], v[36:39]
	v_mfma_f32_16x16x32_bf16 v[32:35], v[174:177], v[216:219], v[32:35]
	s_setprio 0
	s_barrier
; #define PG8_STAGE(bufoff, gbase, voff) do { _Pragma("unroll") for (int _i = 0; _i < 2; ++_i) \
;         __builtin_amdgcn_global_load_lds((const unsigned*)((const char*)(gbase) + (voff)[_i]), (PG8_LAS unsigned*)(lds + (bufoff) + ldsw + _i * 8192), 16, 0, 0); } while (0)
; #define PG8_LDA(dst, b, h) do { _Pragma("unroll") for (int m = 0; m < 4; ++m) _Pragma("unroll") for (int k = 0; k < 2; ++k) dst[m][k] = *(const PG8_LAS bf16x8*)(lds + PG8_SA(b, h) + aoff + m * 2048 + k * 1024); } while (0)
; #define PG8_MMA(ai, bj, At, Bt) do { __builtin_amdgcn_s_setprio(1); _Pragma("unroll") for (int m = 0; m < 4; ++m) _Pragma("unroll") for (int n = 0; n < 2; ++n) _Pragma("unroll") for (int k = 0; k < 2; ++k) \
;         acc[ai][bj][m][n] = __builtin_amdgcn_mfma_f32_16x16x32_bf16(Bt[n][k], At[m][k], acc[ai][bj][m][n], 0, 0, 0); __builtin_amdgcn_s_setprio(0); } while (0)
; #define PG8_WAIT_V(n) asm volatile("s_waitcnt vmcnt(" #n ")" ::: "memory")
; #define PG8_WAIT_L(n) asm volatile("s_waitcnt lgkmcnt(" #n ")" ::: "memory")
; #define PG8_BAR __builtin_amdgcn_s_barrier()
; #define PG8_SCHED __builtin_amdgcn_sched_barrier(0)
; template <class Epi, class Sched, bool ALIGN_EPI = false, bool SP2 = false>
; __device__ __forceinline__ void gemm_phase(PG8_LAS unsigned char* lds, const Gemm g, const Sched& S, const Epi& E, int tid_in) {
;     ...
;             PG8_LDA(At, 1, 1); PG8_STAGE(PG8_SB(1, 0), b3, voffB); PG8_STAGE(PG8_SB(1, 1), b3 + hstep, voffB); PG8_STAGE(PG8_SA(1, 0), a3, voffA);
;             PG8_WAIT_V(8); PG8_WAIT_L(0); PG8_BAR; PG8_MMA(1, 0, At, B0); PG8_MMA(1, 1, At, B1); PG8_BAR; PG8_SCHED;
	s_add_i32 s28, s54, s35
	s_mov_b32 m0, s28
	ds_read_b128 v[178:181], v157 offset:49152
	ds_read_b128 v[182:185], v157 offset:50176
	ds_read_b128 v[186:189], v157 offset:51200
	ds_read_b128 v[200:203], v157 offset:52224
	ds_read_b128 v[204:207], v157 offset:53248
	ds_read_b128 v[208:211], v157 offset:54272
	ds_read_b128 v[212:215], v157 offset:55296
	ds_read_b128 v[216:219], v157 offset:56320
	s_add_u32 s100, s100, 0x80
	s_addc_u32 s101, s101, 0
	global_load_lds_dwordx4 v190, s[100:101]
	s_add_i32 m0, s28, 0x2000
	s_add_u32 s26, s26, 0x80080
	s_addc_u32 s27, s27, 0
	s_add_i32 s28, s55, s35
	global_load_lds_dwordx4 v136, s[100:101]
	s_mov_b32 m0, s28
	s_nop 0
	global_load_lds_dwordx4 v190, s[26:27]
	s_add_i32 m0, s28, 0x2000
	s_nop 0
	global_load_lds_dwordx4 v136, s[26:27]
	v_lshl_add_u64 v[226:227], v[230:231], 0, s[0:1]
	s_mov_b32 m0, s45
	s_nop 0
	global_load_lds_dwordx4 v[226:227], off
	v_lshl_add_u64 v[226:227], v[232:233], 0, s[0:1]
	s_mov_b32 m0, s46
	s_nop 0
	global_load_lds_dwordx4 v[226:227], off
	s_waitcnt vmcnt(8)
	s_waitcnt lgkmcnt(0)
	s_barrier
	s_setprio 1
	s_waitcnt lgkmcnt(0)
	v_mfma_f32_16x16x32_bf16 v[92:95], v[96:99], v[178:181], v[92:95]
	v_mfma_f32_16x16x32_bf16 v[88:91], v[150:153], v[178:181], v[88:91]
	v_mfma_f32_16x16x32_bf16 v[84:87], v[96:99], v[186:189], v[84:87]
	v_mfma_f32_16x16x32_bf16 v[80:83], v[150:153], v[186:189], v[80:83]
	v_mfma_f32_16x16x32_bf16 v[76:79], v[96:99], v[204:207], v[76:79]
	v_mfma_f32_16x16x32_bf16 v[72:75], v[150:153], v[204:207], v[72:75]
	v_mfma_f32_16x16x32_bf16 v[68:71], v[96:99], v[212:215], v[68:71]
	v_mfma_f32_16x16x32_bf16 v[64:67], v[150:153], v[212:215], v[64:67]
	v_mfma_f32_16x16x32_bf16 v[92:95], v[100:103], v[182:185], v[92:95]
	v_mfma_f32_16x16x32_bf16 v[88:91], v[158:161], v[182:185], v[88:91]
	v_mfma_f32_16x16x32_bf16 v[84:87], v[100:103], v[200:203], v[84:87]
	v_mfma_f32_16x16x32_bf16 v[80:83], v[158:161], v[200:203], v[80:83]
	v_mfma_f32_16x16x32_bf16 v[76:79], v[100:103], v[208:211], v[76:79]
	v_mfma_f32_16x16x32_bf16 v[72:75], v[158:161], v[208:211], v[72:75]
	v_mfma_f32_16x16x32_bf16 v[68:71], v[100:103], v[216:219], v[68:71]
	v_mfma_f32_16x16x32_bf16 v[64:67], v[158:161], v[216:219], v[64:67]
	s_setprio 0
	s_setprio 1
	v_mfma_f32_16x16x32_bf16 v[28:31], v[162:165], v[178:181], v[28:31]
	v_mfma_f32_16x16x32_bf16 v[24:27], v[170:173], v[178:181], v[24:27]
	v_mfma_f32_16x16x32_bf16 v[20:23], v[162:165], v[186:189], v[20:23]
	v_mfma_f32_16x16x32_bf16 v[16:19], v[170:173], v[186:189], v[16:19]
	v_mfma_f32_16x16x32_bf16 v[12:15], v[162:165], v[204:207], v[12:15]
	v_mfma_f32_16x16x32_bf16 v[8:11], v[170:173], v[204:207], v[8:11]
	v_mfma_f32_16x16x32_bf16 v[4:7], v[162:165], v[212:215], v[4:7]
	v_mfma_f32_16x16x32_bf16 v[0:3], v[170:173], v[212:215], v[0:3]
	v_mfma_f32_16x16x32_bf16 v[28:31], v[166:169], v[182:185], v[28:31]
	v_mfma_f32_16x16x32_bf16 v[24:27], v[174:177], v[182:185], v[24:27]
	v_mfma_f32_16x16x32_bf16 v[20:23], v[166:169], v[200:203], v[20:23]
	v_mfma_f32_16x16x32_bf16 v[16:19], v[174:177], v[200:203], v[16:19]
	v_mfma_f32_16x16x32_bf16 v[12:15], v[166:169], v[208:211], v[12:15]
	v_mfma_f32_16x16x32_bf16 v[8:11], v[174:177], v[208:211], v[8:11]
	v_mfma_f32_16x16x32_bf16 v[4:7], v[166:169], v[216:219], v[4:7]
	v_mfma_f32_16x16x32_bf16 v[0:3], v[174:177], v[216:219], v[0:3]
	s_setprio 0
	s_barrier
	s_add_i32 s53, s53, 2
	s_add_u32 s51, s51, 0x100
	s_addc_u32 s52, s52, 0
	s_add_u32 s24, s24, 0x100
	s_addc_u32 s25, s25, 0
	s_cmp_gt_u32 s53, 29
	s_cbranch_scc0 .LBB0_782
	s_and_b64 vcc, exec, s[8:9]
	s_cbranch_vccz .LBB0_785
	s_barrier

; #define PG8_STAGE(bufoff, gbase, voff) do { _Pragma("unroll") for (int _i = 0; _i < 2; ++_i) \
;         __builtin_amdgcn_global_load_lds((const unsigned*)((const char*)(gbase) + (voff)[_i]), (PG8_LAS unsigned*)(lds + (bufoff) + ldsw + _i * 8192), 16, 0, 0); } while (0)
; #define PG8_LDA(dst, b, h) do { _Pragma("unroll") for (int m = 0; m < 4; ++m) _Pragma("unroll") for (int k = 0; k < 2; ++k) dst[m][k] = *(const PG8_LAS bf16x8*)(lds + PG8_SA(b, h) + aoff + m * 2048 + k * 1024); } while (0)
; #define PG8_LDB(dst, b, h) do { _Pragma("unroll") for (int n = 0; n < 2; ++n) _Pragma("unroll") for (int k = 0; k < 2; ++k) dst[n][k] = *(const PG8_LAS bf16x8*)(lds + PG8_SB(b, h) + boff + n * 2048 + k * 1024); } while (0)
; #define PG8_MMA(ai, bj, At, Bt) do { __builtin_amdgcn_s_setprio(1); _Pragma("unroll") for (int m = 0; m < 4; ++m) _Pragma("unroll") for (int n = 0; n < 2; ++n) _Pragma("unroll") for (int k = 0; k < 2; ++k) \
;         acc[ai][bj][m][n] = __builtin_amdgcn_mfma_f32_16x16x32_bf16(Bt[n][k], At[m][k], acc[ai][bj][m][n], 0, 0, 0); __builtin_amdgcn_s_setprio(0); } while (0)
; #define PG8_WAIT_V(n) asm volatile("s_waitcnt vmcnt(" #n ")" ::: "memory")
; #define PG8_WAIT_L(n) asm volatile("s_waitcnt lgkmcnt(" #n ")" ::: "memory")
; template <class Epi, class Sched, bool ALIGN_EPI = false, bool SP2 = false>
; __device__ __forceinline__ void gemm_phase(PG8_LAS unsigned char* lds, const Gemm g, const Sched& S, const Epi& E, int tid_in) {
;     ...
;             const bool last = (t == nt - 2);
;             const char* a1 = cA + (size_t)(t + 1) * kstep;
;             const char* a2 = last ? nA : cA + (size_t)(t + 2) * kstep; const char* b2 = last ? nB : cB + (size_t)(t + 2) * kstep;
;             const char* a3 = a2 + kstep; const char* b3 = b2 + kstep;
;             if (last && has_next) S.a_ready(nxt);
;             if constexpr (SP2) {
;             PG8_LDB(B0, 0, 0); PG8_LDB(B1, 0, 1); PG8_SCHED; PG8_LDA(At, 0, 0); PG8_STAGE(PG8_SA(1, 1), a1 + hstepA, voffA);
;             PG8_WAIT_V(8); PG8_WAIT_L(0); PG8_BAR; PG8_MMA(0, 0, At, B0); PG8_MMA(0, 1, At, B1); PG8_BAR; PG8_SCHED;
;             PG8_LDA(At, 0, 1); PG8_STAGE(PG8_SB(0, 0), b2, voffB); PG8_STAGE(PG8_SB(0, 1), b2 + hstep, voffB); PG8_STAGE(PG8_SA(0, 0), a2, voffA);
;             PG8_WAIT_V(8); PG8_WAIT_L(0); PG8_BAR; PG8_MMA(1, 0, At, B0); PG8_MMA(1, 1, At, B1); PG8_BAR; PG8_SCHED;
.LBB0_1283:
	s_add_u32 s14, s12, 0xfffc0080
	s_addc_u32 s15, s13, -1
	s_add_i32 s60, 0, 0x10000
	s_cmp_eq_u32 s59, 12
	s_cselect_b32 s27, s19, s15
	s_cselect_b32 s26, s55, s14
	s_cselect_b32 s15, s11, s58
	s_cselect_b32 s14, s56, s57
	s_add_i32 s62, 0, 0x14000
	v_add_u32_e32 v124, s60, v226
	v_add_u32_e32 v140, s62, v226
	ds_read_b128 v[112:115], v124
	ds_read_b128 v[116:119], v124 offset:1024
	ds_read_b128 v[120:123], v124 offset:2048
	ds_read_b128 v[124:127], v124 offset:3072
	ds_read_b128 v[128:131], v140
	ds_read_b128 v[132:135], v140 offset:1024
	ds_read_b128 v[136:139], v140 offset:2048
	ds_read_b128 v[140:143], v140 offset:3072
	s_add_i32 m0, s35, 0xc000
	ds_read_b128 v[144:147], v227
	ds_read_b128 v[148:151], v227 offset:1024
	ds_read_b128 v[152:155], v227 offset:2048
	ds_read_b128 v[156:159], v227 offset:3072
	ds_read_b128 v[176:179], v227 offset:4096
	ds_read_b128 v[180:183], v227 offset:5120
	ds_read_b128 v[208:211], v227 offset:6144
	ds_read_b128 v[212:215], v227 offset:7168
	global_load_lds_dwordx4 v206, s[12:13]
	s_add_i32 m0, s35, 0xe000
	s_nop 0
	global_load_lds_dwordx4 v204, s[12:13]
	s_waitcnt vmcnt(8)
	s_waitcnt lgkmcnt(0)
	s_barrier
	s_setprio 1
	s_waitcnt lgkmcnt(0)
	v_mfma_f32_16x16x32_bf16 v[172:175], v[112:115], v[144:147], v[172:175]
	v_mfma_f32_16x16x32_bf16 v[168:171], v[120:123], v[144:147], v[168:171]
	v_mfma_f32_16x16x32_bf16 v[108:111], v[112:115], v[152:155], v[108:111]
	v_mfma_f32_16x16x32_bf16 v[104:107], v[120:123], v[152:155], v[104:107]
	v_mfma_f32_16x16x32_bf16 v[92:95], v[112:115], v[176:179], v[92:95]
	v_mfma_f32_16x16x32_bf16 v[88:91], v[120:123], v[176:179], v[88:91]
	v_mfma_f32_16x16x32_bf16 v[76:79], v[112:115], v[208:211], v[76:79]
	v_mfma_f32_16x16x32_bf16 v[72:75], v[120:123], v[208:211], v[72:75]
	v_mfma_f32_16x16x32_bf16 v[172:175], v[116:119], v[148:151], v[172:175]
	v_mfma_f32_16x16x32_bf16 v[168:171], v[124:127], v[148:151], v[168:171]
	v_mfma_f32_16x16x32_bf16 v[108:111], v[116:119], v[156:159], v[108:111]
	v_mfma_f32_16x16x32_bf16 v[104:107], v[124:127], v[156:159], v[104:107]
	v_mfma_f32_16x16x32_bf16 v[92:95], v[116:119], v[180:183], v[92:95]
	v_mfma_f32_16x16x32_bf16 v[88:91], v[124:127], v[180:183], v[88:91]
	v_mfma_f32_16x16x32_bf16 v[76:79], v[116:119], v[212:215], v[76:79]
	v_mfma_f32_16x16x32_bf16 v[72:75], v[124:127], v[212:215], v[72:75]
	s_setprio 0
	s_setprio 1
	v_mfma_f32_16x16x32_bf16 v[164:167], v[128:131], v[144:147], v[164:167]
	v_mfma_f32_16x16x32_bf16 v[100:103], v[128:131], v[152:155], v[100:103]
	v_mfma_f32_16x16x32_bf16 v[96:99], v[136:139], v[152:155], v[96:99]
	v_mfma_f32_16x16x32_bf16 v[84:87], v[128:131], v[176:179], v[84:87]
	v_mfma_f32_16x16x32_bf16 v[80:83], v[136:139], v[176:179], v[80:83]
	v_mfma_f32_16x16x32_bf16 v[68:71], v[128:131], v[208:211], v[68:71]
	v_mfma_f32_16x16x32_bf16 v[64:67], v[136:139], v[208:211], v[64:67]
	v_mfma_f32_16x16x32_bf16 v[164:167], v[132:135], v[148:151], v[164:167]
	v_mfma_f32_16x16x32_bf16 v[144:147], v[136:139], v[144:147], v[160:163]
	v_mfma_f32_16x16x32_bf16 v[100:103], v[132:135], v[156:159], v[100:103]
	v_mfma_f32_16x16x32_bf16 v[96:99], v[140:143], v[156:159], v[96:99]
	v_mfma_f32_16x16x32_bf16 v[84:87], v[132:135], v[180:183], v[84:87]
	v_mfma_f32_16x16x32_bf16 v[80:83], v[140:143], v[180:183], v[80:83]
	v_mfma_f32_16x16x32_bf16 v[68:71], v[132:135], v[212:215], v[68:71]
	v_mfma_f32_16x16x32_bf16 v[64:67], v[140:143], v[212:215], v[64:67]
	v_mfma_f32_16x16x32_bf16 v[144:147], v[140:143], v[148:151], v[144:147]
	s_setprio 0
	s_barrier
	s_add_i32 s60, s60, s34
	s_mov_b32 m0, s60
	ds_read_b128 v[148:151], v227 offset:16384
	ds_read_b128 v[152:155], v227 offset:17408
	ds_read_b128 v[156:159], v227 offset:18432
	ds_read_b128 v[160:163], v227 offset:19456
	ds_read_b128 v[176:179], v227 offset:20480
	ds_read_b128 v[180:183], v227 offset:21504
	ds_read_b128 v[208:211], v227 offset:22528
	ds_read_b128 v[212:215], v227 offset:23552
	global_load_lds_dwordx4 v190, s[14:15]
	s_add_i32 m0, s60, 0x2000
	s_add_u32 s60, s14, 0x40000
	s_addc_u32 s61, s15, 0
	s_add_i32 s62, s62, s34
	global_load_lds_dwordx4 v184, s[14:15]
	s_mov_b32 m0, s62
	s_mov_b64 s[100:101], s[26:27]
	global_load_lds_dwordx4 v190, s[60:61]
	s_add_i32 m0, s62, 0x2000
	s_nop 0
	global_load_lds_dwordx4 v184, s[60:61]
	s_mov_b32 m0, s35
	s_nop 0
	global_load_lds_dwordx4 v188, s[100:101]
	s_mov_b32 m0, s46
	s_nop 0
	global_load_lds_dwordx4 v186, s[100:101]
	s_waitcnt vmcnt(8)
	s_waitcnt lgkmcnt(0)
	s_barrier
	s_setprio 1
	s_waitcnt lgkmcnt(0)
	v_mfma_f32_16x16x32_bf16 v[60:63], v[112:115], v[148:151], v[60:63]
	v_mfma_f32_16x16x32_bf16 v[56:59], v[120:123], v[148:151], v[56:59]
	v_mfma_f32_16x16x32_bf16 v[44:47], v[112:115], v[156:159], v[44:47]
	v_mfma_f32_16x16x32_bf16 v[40:43], v[120:123], v[156:159], v[40:43]
	v_mfma_f32_16x16x32_bf16 v[28:31], v[112:115], v[176:179], v[28:31]
	v_mfma_f32_16x16x32_bf16 v[24:27], v[120:123], v[176:179], v[24:27]
	v_mfma_f32_16x16x32_bf16 v[12:15], v[112:115], v[208:211], v[12:15]
	v_mfma_f32_16x16x32_bf16 v[8:11], v[120:123], v[208:211], v[8:11]
	v_mfma_f32_16x16x32_bf16 v[60:63], v[116:119], v[152:155], v[60:63]
	v_mfma_f32_16x16x32_bf16 v[56:59], v[124:127], v[152:155], v[56:59]
	v_mfma_f32_16x16x32_bf16 v[44:47], v[116:119], v[160:163], v[44:47]
	v_mfma_f32_16x16x32_bf16 v[40:43], v[124:127], v[160:163], v[40:43]
	v_mfma_f32_16x16x32_bf16 v[28:31], v[116:119], v[180:183], v[28:31]
	v_mfma_f32_16x16x32_bf16 v[24:27], v[124:127], v[180:183], v[24:27]
	v_mfma_f32_16x16x32_bf16 v[12:15], v[116:119], v[212:215], v[12:15]
	v_mfma_f32_16x16x32_bf16 v[8:11], v[124:127], v[212:215], v[8:11]
	s_setprio 0
	s_setprio 1
	v_mfma_f32_16x16x32_bf16 v[52:55], v[128:131], v[148:151], v[52:55]
	v_mfma_f32_16x16x32_bf16 v[48:51], v[136:139], v[148:151], v[48:51]
	v_mfma_f32_16x16x32_bf16 v[36:39], v[128:131], v[156:159], v[36:39]
	v_mfma_f32_16x16x32_bf16 v[32:35], v[136:139], v[156:159], v[32:35]
	v_mfma_f32_16x16x32_bf16 v[20:23], v[128:131], v[176:179], v[20:23]
	v_mfma_f32_16x16x32_bf16 v[16:19], v[136:139], v[176:179], v[16:19]
	v_mfma_f32_16x16x32_bf16 v[4:7], v[128:131], v[208:211], v[4:7]
	v_mfma_f32_16x16x32_bf16 v[0:3], v[136:139], v[208:211], v[0:3]
	v_mfma_f32_16x16x32_bf16 v[52:55], v[132:135], v[152:155], v[52:55]
	v_mfma_f32_16x16x32_bf16 v[48:51], v[140:143], v[152:155], v[48:51]
	v_mfma_f32_16x16x32_bf16 v[36:39], v[132:135], v[160:163], v[36:39]
	v_mfma_f32_16x16x32_bf16 v[32:35], v[140:143], v[160:163], v[32:35]
	v_mfma_f32_16x16x32_bf16 v[20:23], v[132:135], v[180:183], v[20:23]
	v_mfma_f32_16x16x32_bf16 v[16:19], v[140:143], v[180:183], v[16:19]
	v_mfma_f32_16x16x32_bf16 v[4:7], v[132:135], v[212:215], v[4:7]
	v_mfma_f32_16x16x32_bf16 v[0:3], v[140:143], v[212:215], v[0:3]
	s_setprio 0
	s_barrier
; #define PG8_STAGE(bufoff, gbase, voff) do { _Pragma("unroll") for (int _i = 0; _i < 2; ++_i) \
;         __builtin_amdgcn_global_load_lds((const unsigned*)((const char*)(gbase) + (voff)[_i]), (PG8_LAS unsigned*)(lds + (bufoff) + ldsw + _i * 8192), 16, 0, 0); } while (0)
; #define PG8_LDA(dst, b, h) do { _Pragma("unroll") for (int m = 0; m < 4; ++m) _Pragma("unroll") for (int k = 0; k < 2; ++k) dst[m][k] = *(const PG8_LAS bf16x8*)(lds + PG8_SA(b, h) + aoff + m * 2048 + k * 1024); } while (0)
; #define PG8_LDB(dst, b, h) do { _Pragma("unroll") for (int n = 0; n < 2; ++n) _Pragma("unroll") for (int k = 0; k < 2; ++k) dst[n][k] = *(const PG8_LAS bf16x8*)(lds + PG8_SB(b, h) + boff + n * 2048 + k * 1024); } while (0)
; #define PG8_MMA(ai, bj, At, Bt) do { __builtin_amdgcn_s_setprio(1); _Pragma("unroll") for (int m = 0; m < 4; ++m) _Pragma("unroll") for (int n = 0; n < 2; ++n) _Pragma("unroll") for (int k = 0; k < 2; ++k) \
;         acc[ai][bj][m][n] = __builtin_amdgcn_mfma_f32_16x16x32_bf16(Bt[n][k], At[m][k], acc[ai][bj][m][n], 0, 0, 0); __builtin_amdgcn_s_setprio(0); } while (0)
; #define PG8_WAIT_V(n) asm volatile("s_waitcnt vmcnt(" #n ")" ::: "memory")
; #define PG8_WAIT_L(n) asm volatile("s_waitcnt lgkmcnt(" #n ")" ::: "memory")
; #define PG8_BAR __builtin_amdgcn_s_barrier()
; #define PG8_SCHED __builtin_amdgcn_sched_barrier(0)
; template <class Epi, class Sched, bool ALIGN_EPI = false, bool SP2 = false>
; __device__ __forceinline__ void gemm_phase(PG8_LAS unsigned char* lds, const Gemm g, const Sched& S, const Epi& E, int tid_in) {
;     ...
;             PG8_LDB(B0, 1, 0); PG8_LDB(B1, 1, 1); PG8_SCHED; PG8_LDA(At, 1, 0); PG8_STAGE(PG8_SA(0, 1), a2 + hstepA, voffA);
;             PG8_WAIT_V(8); PG8_WAIT_L(0); PG8_BAR; PG8_MMA(0, 0, At, B0); PG8_MMA(0, 1, At, B1); PG8_BAR; PG8_SCHED;
;             PG8_LDA(At, 1, 1); PG8_STAGE(PG8_SB(1, 0), b3, voffB); PG8_STAGE(PG8_SB(1, 1), b3 + hstep, voffB); PG8_STAGE(PG8_SA(1, 0), a3, voffA);
;             PG8_WAIT_V(8); PG8_WAIT_L(0); PG8_BAR; PG8_MMA(1, 0, At, B0); PG8_MMA(1, 1, At, B1); PG8_BAR; PG8_SCHED;
	s_add_i32 s60, 0, 0x18000
	s_add_i32 s61, 0, 0x1c000
	v_add_u32_e32 v124, s60, v226
	v_add_u32_e32 v140, s61, v226
	ds_read_b128 v[112:115], v124
	ds_read_b128 v[116:119], v124 offset:1024
	ds_read_b128 v[120:123], v124 offset:2048
	ds_read_b128 v[124:127], v124 offset:3072
	ds_read_b128 v[128:131], v140
	ds_read_b128 v[132:135], v140 offset:1024
	ds_read_b128 v[136:139], v140 offset:2048
	ds_read_b128 v[140:143], v140 offset:3072
	s_add_u32 s26, s26, 0x40000
	s_addc_u32 s27, s27, 0
	s_mov_b32 m0, s47
	ds_read_b128 v[148:151], v227 offset:32768
	ds_read_b128 v[152:155], v227 offset:33792
	ds_read_b128 v[156:159], v227 offset:34816
	ds_read_b128 v[176:179], v227 offset:35840
	ds_read_b128 v[180:183], v227 offset:36864
	ds_read_b128 v[208:211], v227 offset:37888
	ds_read_b128 v[212:215], v227 offset:38912
	ds_read_b128 v[216:219], v227 offset:39936
	global_load_lds_dwordx4 v188, s[26:27]
	s_mov_b32 m0, s49
	s_nop 0
	global_load_lds_dwordx4 v186, s[26:27]
	s_waitcnt vmcnt(8)
	s_waitcnt lgkmcnt(0)
	s_barrier
	s_setprio 1
	s_waitcnt lgkmcnt(0)
	v_mfma_f32_16x16x32_bf16 v[160:163], v[112:115], v[148:151], v[172:175]
	v_mfma_f32_16x16x32_bf16 v[172:175], v[116:119], v[152:155], v[160:163]
	v_mfma_f32_16x16x32_bf16 v[160:163], v[120:123], v[148:151], v[168:171]
	v_mfma_f32_16x16x32_bf16 v[108:111], v[112:115], v[156:159], v[108:111]
	v_mfma_f32_16x16x32_bf16 v[104:107], v[120:123], v[156:159], v[104:107]
	v_mfma_f32_16x16x32_bf16 v[92:95], v[112:115], v[180:183], v[92:95]
	v_mfma_f32_16x16x32_bf16 v[88:91], v[120:123], v[180:183], v[88:91]
	v_mfma_f32_16x16x32_bf16 v[76:79], v[112:115], v[212:215], v[76:79]
	v_mfma_f32_16x16x32_bf16 v[72:75], v[120:123], v[212:215], v[72:75]
	v_mfma_f32_16x16x32_bf16 v[168:171], v[124:127], v[152:155], v[160:163]
	v_mfma_f32_16x16x32_bf16 v[108:111], v[116:119], v[176:179], v[108:111]
	v_mfma_f32_16x16x32_bf16 v[104:107], v[124:127], v[176:179], v[104:107]
	v_mfma_f32_16x16x32_bf16 v[92:95], v[116:119], v[208:211], v[92:95]
	v_mfma_f32_16x16x32_bf16 v[88:91], v[124:127], v[208:211], v[88:91]
	v_mfma_f32_16x16x32_bf16 v[76:79], v[116:119], v[216:219], v[76:79]
	v_mfma_f32_16x16x32_bf16 v[72:75], v[124:127], v[216:219], v[72:75]
	s_setprio 0
	s_setprio 1
	v_mfma_f32_16x16x32_bf16 v[160:163], v[128:131], v[148:151], v[164:167]
	v_mfma_f32_16x16x32_bf16 v[144:147], v[136:139], v[148:151], v[144:147]
	v_mfma_f32_16x16x32_bf16 v[100:103], v[128:131], v[156:159], v[100:103]
	v_mfma_f32_16x16x32_bf16 v[96:99], v[136:139], v[156:159], v[96:99]
	v_mfma_f32_16x16x32_bf16 v[84:87], v[128:131], v[180:183], v[84:87]
	v_mfma_f32_16x16x32_bf16 v[80:83], v[136:139], v[180:183], v[80:83]
	v_mfma_f32_16x16x32_bf16 v[68:71], v[128:131], v[212:215], v[68:71]
	v_mfma_f32_16x16x32_bf16 v[64:67], v[136:139], v[212:215], v[64:67]
	v_mfma_f32_16x16x32_bf16 v[164:167], v[132:135], v[152:155], v[160:163]
	v_mfma_f32_16x16x32_bf16 v[160:163], v[140:143], v[152:155], v[144:147]
	v_mfma_f32_16x16x32_bf16 v[100:103], v[132:135], v[176:179], v[100:103]
	v_mfma_f32_16x16x32_bf16 v[96:99], v[140:143], v[176:179], v[96:99]
	v_mfma_f32_16x16x32_bf16 v[84:87], v[132:135], v[208:211], v[84:87]
	v_mfma_f32_16x16x32_bf16 v[80:83], v[140:143], v[208:211], v[80:83]
	v_mfma_f32_16x16x32_bf16 v[68:71], v[132:135], v[216:219], v[68:71]
	v_mfma_f32_16x16x32_bf16 v[64:67], v[140:143], v[216:219], v[64:67]
	s_setprio 0
	s_barrier
	s_add_i32 s26, s60, s34
	s_mov_b32 m0, s26
	ds_read_b128 v[144:147], v227 offset:49152
	ds_read_b128 v[148:151], v227 offset:50176
	ds_read_b128 v[152:155], v227 offset:51200
	ds_read_b128 v[156:159], v227 offset:52224
	ds_read_b128 v[176:179], v227 offset:53248
	ds_read_b128 v[180:183], v227 offset:54272
	ds_read_b128 v[208:211], v227 offset:55296
	ds_read_b128 v[212:215], v227 offset:56320
	s_add_u32 s14, s14, 0x80
	s_addc_u32 s15, s15, 0
	global_load_lds_dwordx4 v190, s[14:15]
	s_add_i32 m0, s26, 0x2000
	s_nop 0
	global_load_lds_dwordx4 v184, s[14:15]
	s_add_u32 s14, s14, 0x40000
	s_addc_u32 s15, s15, 0
	s_add_i32 s26, s61, s34
	s_mov_b32 m0, s26
	s_nop 0
	global_load_lds_dwordx4 v190, s[14:15]
	s_add_i32 m0, s26, 0x2000
	s_nop 0
	global_load_lds_dwordx4 v184, s[14:15]
	s_mov_b32 m0, s52
	s_nop 0
	s_add_u32 s100, s100, 0x80
	s_addc_u32 s101, s101, 0
	global_load_lds_dwordx4 v188, s[100:101]
	s_mov_b32 m0, s53
	s_nop 0
	global_load_lds_dwordx4 v186, s[100:101]
	s_waitcnt vmcnt(8)
	s_waitcnt lgkmcnt(0)
	s_barrier
	s_setprio 1
	s_waitcnt lgkmcnt(0)
	v_mfma_f32_16x16x32_bf16 v[60:63], v[112:115], v[144:147], v[60:63]
	v_mfma_f32_16x16x32_bf16 v[56:59], v[120:123], v[144:147], v[56:59]
	v_mfma_f32_16x16x32_bf16 v[44:47], v[112:115], v[152:155], v[44:47]
	v_mfma_f32_16x16x32_bf16 v[40:43], v[120:123], v[152:155], v[40:43]
	v_mfma_f32_16x16x32_bf16 v[28:31], v[112:115], v[176:179], v[28:31]
	v_mfma_f32_16x16x32_bf16 v[24:27], v[120:123], v[176:179], v[24:27]
	v_mfma_f32_16x16x32_bf16 v[12:15], v[112:115], v[208:211], v[12:15]
	v_mfma_f32_16x16x32_bf16 v[8:11], v[120:123], v[208:211], v[8:11]
	v_mfma_f32_16x16x32_bf16 v[60:63], v[116:119], v[148:151], v[60:63]
	v_mfma_f32_16x16x32_bf16 v[56:59], v[124:127], v[148:151], v[56:59]
	v_mfma_f32_16x16x32_bf16 v[44:47], v[116:119], v[156:159], v[44:47]
	v_mfma_f32_16x16x32_bf16 v[40:43], v[124:127], v[156:159], v[40:43]
	v_mfma_f32_16x16x32_bf16 v[28:31], v[116:119], v[180:183], v[28:31]
	v_mfma_f32_16x16x32_bf16 v[24:27], v[124:127], v[180:183], v[24:27]
	v_mfma_f32_16x16x32_bf16 v[12:15], v[116:119], v[212:215], v[12:15]
	v_mfma_f32_16x16x32_bf16 v[8:11], v[124:127], v[212:215], v[8:11]
	s_setprio 0
	s_setprio 1
	v_mfma_f32_16x16x32_bf16 v[52:55], v[128:131], v[144:147], v[52:55]
	v_mfma_f32_16x16x32_bf16 v[48:51], v[136:139], v[144:147], v[48:51]
	v_mfma_f32_16x16x32_bf16 v[36:39], v[128:131], v[152:155], v[36:39]
	v_mfma_f32_16x16x32_bf16 v[32:35], v[136:139], v[152:155], v[32:35]
	v_mfma_f32_16x16x32_bf16 v[20:23], v[128:131], v[176:179], v[20:23]
	v_mfma_f32_16x16x32_bf16 v[16:19], v[136:139], v[176:179], v[16:19]
	v_mfma_f32_16x16x32_bf16 v[4:7], v[128:131], v[208:211], v[4:7]
	v_mfma_f32_16x16x32_bf16 v[0:3], v[136:139], v[208:211], v[0:3]
	v_mfma_f32_16x16x32_bf16 v[52:55], v[132:135], v[148:151], v[52:55]
	v_mfma_f32_16x16x32_bf16 v[48:51], v[140:143], v[148:151], v[48:51]
	v_mfma_f32_16x16x32_bf16 v[36:39], v[132:135], v[156:159], v[36:39]
	v_mfma_f32_16x16x32_bf16 v[32:35], v[140:143], v[156:159], v[32:35]
	v_mfma_f32_16x16x32_bf16 v[20:23], v[132:135], v[180:183], v[20:23]
	v_mfma_f32_16x16x32_bf16 v[16:19], v[140:143], v[180:183], v[16:19]
	v_mfma_f32_16x16x32_bf16 v[4:7], v[132:135], v[212:215], v[4:7]
	v_mfma_f32_16x16x32_bf16 v[0:3], v[140:143], v[212:215], v[0:3]
	s_setprio 0
	s_barrier
	s_add_i32 s59, s59, 2
	s_add_u32 s57, s57, 0x100
	s_addc_u32 s58, s58, 0
	s_add_u32 s12, s12, 0x100
	s_addc_u32 s13, s13, 0
	s_cmp_gt_u32 s59, 13
	s_cbranch_scc0 .LBB0_1283
	s_and_b64 vcc, exec, s[8:9]
	s_cbranch_vccz .LBB0_1286
	s_barrier

; #define PG8_STAGE(bufoff, gbase, voff) do { _Pragma("unroll") for (int _i = 0; _i < 2; ++_i) \
;         __builtin_amdgcn_global_load_lds((const unsigned*)((const char*)(gbase) + (voff)[_i]), (PG8_LAS unsigned*)(lds + (bufoff) + ldsw + _i * 8192), 16, 0, 0); } while (0)
; #define PG8_LDA(dst, b, h) do { _Pragma("unroll") for (int m = 0; m < 4; ++m) _Pragma("unroll") for (int k = 0; k < 2; ++k) dst[m][k] = *(const PG8_LAS bf16x8*)(lds + PG8_SA(b, h) + aoff + m * 2048 + k * 1024); } while (0)
; #define PG8_LDB(dst, b, h) do { _Pragma("unroll") for (int n = 0; n < 2; ++n) _Pragma("unroll") for (int k = 0; k < 2; ++k) dst[n][k] = *(const PG8_LAS bf16x8*)(lds + PG8_SB(b, h) + boff + n * 2048 + k * 1024); } while (0)
; #define PG8_MMA(ai, bj, At, Bt) do { __builtin_amdgcn_s_setprio(1); _Pragma("unroll") for (int m = 0; m < 4; ++m) _Pragma("unroll") for (int n = 0; n < 2; ++n) _Pragma("unroll") for (int k = 0; k < 2; ++k) \
;         acc[ai][bj][m][n] = __builtin_amdgcn_mfma_f32_16x16x32_bf16(Bt[n][k], At[m][k], acc[ai][bj][m][n], 0, 0, 0); __builtin_amdgcn_s_setprio(0); } while (0)
; #define PG8_WAIT_V(n) asm volatile("s_waitcnt vmcnt(" #n ")" ::: "memory")
; #define PG8_WAIT_L(n) asm volatile("s_waitcnt lgkmcnt(" #n ")" ::: "memory")
; template <class Epi, class Sched, bool ALIGN_EPI = false, bool SP2 = false>
; __device__ __forceinline__ void gemm_phase(PG8_LAS unsigned char* lds, const Gemm g, const Sched& S, const Epi& E, int tid_in) {
;     ...
;             const bool last = (t == nt - 2);
;             const char* a1 = cA + (size_t)(t + 1) * kstep;
;             const char* a2 = last ? nA : cA + (size_t)(t + 2) * kstep; const char* b2 = last ? nB : cB + (size_t)(t + 2) * kstep;
;             const char* a3 = a2 + kstep; const char* b3 = b2 + kstep;
;             if (last && has_next) S.a_ready(nxt);
;             if constexpr (SP2) {
;             PG8_LDB(B0, 0, 0); PG8_LDB(B1, 0, 1); PG8_SCHED; PG8_LDA(At, 0, 0); PG8_STAGE(PG8_SA(1, 1), a1 + hstepA, voffA);
;             PG8_WAIT_V(8); PG8_WAIT_L(0); PG8_BAR; PG8_MMA(0, 0, At, B0); PG8_MMA(0, 1, At, B1); PG8_BAR; PG8_SCHED;
;             PG8_LDA(At, 0, 1); PG8_STAGE(PG8_SB(0, 0), b2, voffB); PG8_STAGE(PG8_SB(0, 1), b2 + hstep, voffB); PG8_STAGE(PG8_SA(0, 0), a2, voffA);
;             PG8_WAIT_V(8); PG8_WAIT_L(0); PG8_BAR; PG8_MMA(1, 0, At, B0); PG8_MMA(1, 1, At, B1); PG8_BAR; PG8_SCHED;
.LBB0_1385:
	s_add_u32 s12, s2, 0xfffc0080
	s_addc_u32 s13, s3, -1
	s_add_i32 s58, 0, 0x10000
	s_cmp_eq_u32 s57, 12
	s_cselect_b32 s15, s21, s13
	s_cselect_b32 s14, s53, s12
	v_add_u32_e32 v140, s58, v145
	s_cselect_b32 s13, s19, s56
	s_cselect_b32 s12, s54, s55
	s_add_i32 s60, 0, 0x14000
	ds_read_b128 v[148:151], v140
	ds_read_b128 v[152:155], v140 offset:1024
	ds_read_b128 v[156:159], v140 offset:2048
	ds_read_b128 v[160:163], v140 offset:3072
	v_add_u32_e32 v140, s60, v145
	ds_read_b128 v[164:167], v140
	ds_read_b128 v[168:171], v140 offset:1024
	ds_read_b128 v[172:175], v140 offset:2048
	ds_read_b128 v[176:179], v140 offset:3072
	s_add_i32 m0, s45, 0xc000
	ds_read_b128 v[180:183], v146
	ds_read_b128 v[184:187], v146 offset:1024
	ds_read_b128 v[200:203], v146 offset:2048
	ds_read_b128 v[204:207], v146 offset:3072
	ds_read_b128 v[208:211], v146 offset:4096
	ds_read_b128 v[212:215], v146 offset:5120
	ds_read_b128 v[216:219], v146 offset:6144
	ds_read_b128 v[226:229], v146 offset:7168
	global_load_lds_dwordx4 v138, s[2:3]
	s_add_i32 m0, s45, 0xe000
	s_nop 0
	global_load_lds_dwordx4 v136, s[2:3]
	s_waitcnt vmcnt(8)
	s_waitcnt lgkmcnt(0)
	s_barrier
	s_setprio 1
	s_waitcnt lgkmcnt(0)
	v_mfma_f32_16x16x32_bf16 v[124:127], v[148:151], v[180:183], v[124:127]
	v_mfma_f32_16x16x32_bf16 v[116:119], v[156:159], v[180:183], v[116:119]
	v_mfma_f32_16x16x32_bf16 v[108:111], v[148:151], v[200:203], v[108:111]
	v_mfma_f32_16x16x32_bf16 v[100:103], v[156:159], v[200:203], v[100:103]
	v_mfma_f32_16x16x32_bf16 v[92:95], v[148:151], v[208:211], v[92:95]
	v_mfma_f32_16x16x32_bf16 v[84:87], v[156:159], v[208:211], v[84:87]
	v_mfma_f32_16x16x32_bf16 v[76:79], v[148:151], v[216:219], v[76:79]
	v_mfma_f32_16x16x32_bf16 v[68:71], v[156:159], v[216:219], v[68:71]
	v_mfma_f32_16x16x32_bf16 v[124:127], v[152:155], v[184:187], v[124:127]
	v_mfma_f32_16x16x32_bf16 v[116:119], v[160:163], v[184:187], v[116:119]
	v_mfma_f32_16x16x32_bf16 v[108:111], v[152:155], v[204:207], v[108:111]
	v_mfma_f32_16x16x32_bf16 v[100:103], v[160:163], v[204:207], v[100:103]
	v_mfma_f32_16x16x32_bf16 v[92:95], v[152:155], v[212:215], v[92:95]
	v_mfma_f32_16x16x32_bf16 v[84:87], v[160:163], v[212:215], v[84:87]
	v_mfma_f32_16x16x32_bf16 v[76:79], v[152:155], v[226:229], v[76:79]
	v_mfma_f32_16x16x32_bf16 v[68:71], v[160:163], v[226:229], v[68:71]
	s_setprio 0
	s_setprio 1
	v_mfma_f32_16x16x32_bf16 v[120:123], v[164:167], v[180:183], v[120:123]
	v_mfma_f32_16x16x32_bf16 v[112:115], v[172:175], v[180:183], v[112:115]
	v_mfma_f32_16x16x32_bf16 v[104:107], v[164:167], v[200:203], v[104:107]
	v_mfma_f32_16x16x32_bf16 v[96:99], v[172:175], v[200:203], v[96:99]
	v_mfma_f32_16x16x32_bf16 v[88:91], v[164:167], v[208:211], v[88:91]
	v_mfma_f32_16x16x32_bf16 v[80:83], v[172:175], v[208:211], v[80:83]
	v_mfma_f32_16x16x32_bf16 v[72:75], v[164:167], v[216:219], v[72:75]
	v_mfma_f32_16x16x32_bf16 v[64:67], v[172:175], v[216:219], v[64:67]
	v_mfma_f32_16x16x32_bf16 v[120:123], v[168:171], v[184:187], v[120:123]
	v_mfma_f32_16x16x32_bf16 v[112:115], v[176:179], v[184:187], v[112:115]
	v_mfma_f32_16x16x32_bf16 v[104:107], v[168:171], v[204:207], v[104:107]
	v_mfma_f32_16x16x32_bf16 v[96:99], v[176:179], v[204:207], v[96:99]
	v_mfma_f32_16x16x32_bf16 v[88:91], v[168:171], v[212:215], v[88:91]
	v_mfma_f32_16x16x32_bf16 v[80:83], v[176:179], v[212:215], v[80:83]
	v_mfma_f32_16x16x32_bf16 v[72:75], v[168:171], v[226:229], v[72:75]
	v_mfma_f32_16x16x32_bf16 v[64:67], v[176:179], v[226:229], v[64:67]
	s_setprio 0
	s_barrier
	s_add_i32 s58, s58, s44
	s_mov_b32 m0, s58
	ds_read_b128 v[180:183], v146 offset:16384
	ds_read_b128 v[184:187], v146 offset:17408
	ds_read_b128 v[200:203], v146 offset:18432
	ds_read_b128 v[204:207], v146 offset:19456
	ds_read_b128 v[208:211], v146 offset:20480
	ds_read_b128 v[212:215], v146 offset:21504
	ds_read_b128 v[216:219], v146 offset:22528
	ds_read_b128 v[226:229], v146 offset:23552
	global_load_lds_dwordx4 v132, s[12:13]
	s_add_i32 m0, s58, 0x2000
	s_add_u32 s58, s12, 0x40000
	s_addc_u32 s59, s13, 0
	s_add_i32 s60, s60, s44
	global_load_lds_dwordx4 v128, s[12:13]
	s_mov_b32 m0, s60
	s_mov_b64 s[100:101], s[14:15]
	global_load_lds_dwordx4 v132, s[58:59]
	s_add_i32 m0, s60, 0x2000
	s_nop 0
	global_load_lds_dwordx4 v128, s[58:59]
	s_mov_b32 m0, s45
	s_nop 0
	global_load_lds_dwordx4 v134, s[100:101]
	s_mov_b32 m0, s46
	s_nop 0
	global_load_lds_dwordx4 v130, s[100:101]
	s_waitcnt vmcnt(8)
	s_waitcnt lgkmcnt(0)
	s_barrier
	s_setprio 1
	s_waitcnt lgkmcnt(0)
	v_mfma_f32_16x16x32_bf16 v[60:63], v[148:151], v[180:183], v[60:63]
	v_mfma_f32_16x16x32_bf16 v[52:55], v[156:159], v[180:183], v[52:55]
	v_mfma_f32_16x16x32_bf16 v[44:47], v[148:151], v[200:203], v[44:47]
	v_mfma_f32_16x16x32_bf16 v[36:39], v[156:159], v[200:203], v[36:39]
	v_mfma_f32_16x16x32_bf16 v[28:31], v[148:151], v[208:211], v[28:31]
	v_mfma_f32_16x16x32_bf16 v[20:23], v[156:159], v[208:211], v[20:23]
	v_mfma_f32_16x16x32_bf16 v[12:15], v[148:151], v[216:219], v[12:15]
	v_mfma_f32_16x16x32_bf16 v[4:7], v[156:159], v[216:219], v[4:7]
	v_mfma_f32_16x16x32_bf16 v[60:63], v[152:155], v[184:187], v[60:63]
	v_mfma_f32_16x16x32_bf16 v[52:55], v[160:163], v[184:187], v[52:55]
	v_mfma_f32_16x16x32_bf16 v[44:47], v[152:155], v[204:207], v[44:47]
	v_mfma_f32_16x16x32_bf16 v[36:39], v[160:163], v[204:207], v[36:39]
	v_mfma_f32_16x16x32_bf16 v[28:31], v[152:155], v[212:215], v[28:31]
	v_mfma_f32_16x16x32_bf16 v[20:23], v[160:163], v[212:215], v[20:23]
	v_mfma_f32_16x16x32_bf16 v[12:15], v[152:155], v[226:229], v[12:15]
	v_mfma_f32_16x16x32_bf16 v[4:7], v[160:163], v[226:229], v[4:7]
	s_setprio 0
	s_setprio 1
	v_mfma_f32_16x16x32_bf16 v[56:59], v[164:167], v[180:183], v[56:59]
	v_mfma_f32_16x16x32_bf16 v[48:51], v[172:175], v[180:183], v[48:51]
	v_mfma_f32_16x16x32_bf16 v[40:43], v[164:167], v[200:203], v[40:43]
	v_mfma_f32_16x16x32_bf16 v[32:35], v[172:175], v[200:203], v[32:35]
	v_mfma_f32_16x16x32_bf16 v[24:27], v[164:167], v[208:211], v[24:27]
	v_mfma_f32_16x16x32_bf16 v[16:19], v[172:175], v[208:211], v[16:19]
	v_mfma_f32_16x16x32_bf16 v[8:11], v[164:167], v[216:219], v[8:11]
	v_mfma_f32_16x16x32_bf16 v[0:3], v[172:175], v[216:219], v[0:3]
	v_mfma_f32_16x16x32_bf16 v[56:59], v[168:171], v[184:187], v[56:59]
	v_mfma_f32_16x16x32_bf16 v[48:51], v[176:179], v[184:187], v[48:51]
	v_mfma_f32_16x16x32_bf16 v[40:43], v[168:171], v[204:207], v[40:43]
	v_mfma_f32_16x16x32_bf16 v[32:35], v[176:179], v[204:207], v[32:35]
	v_mfma_f32_16x16x32_bf16 v[24:27], v[168:171], v[212:215], v[24:27]
	v_mfma_f32_16x16x32_bf16 v[16:19], v[176:179], v[212:215], v[16:19]
	v_mfma_f32_16x16x32_bf16 v[8:11], v[168:171], v[226:229], v[8:11]
	v_mfma_f32_16x16x32_bf16 v[0:3], v[176:179], v[226:229], v[0:3]
	s_setprio 0
	s_barrier
; #define PG8_STAGE(bufoff, gbase, voff) do { _Pragma("unroll") for (int _i = 0; _i < 2; ++_i) \
;         __builtin_amdgcn_global_load_lds((const unsigned*)((const char*)(gbase) + (voff)[_i]), (PG8_LAS unsigned*)(lds + (bufoff) + ldsw + _i * 8192), 16, 0, 0); } while (0)
; #define PG8_LDA(dst, b, h) do { _Pragma("unroll") for (int m = 0; m < 4; ++m) _Pragma("unroll") for (int k = 0; k < 2; ++k) dst[m][k] = *(const PG8_LAS bf16x8*)(lds + PG8_SA(b, h) + aoff + m * 2048 + k * 1024); } while (0)
; #define PG8_LDB(dst, b, h) do { _Pragma("unroll") for (int n = 0; n < 2; ++n) _Pragma("unroll") for (int k = 0; k < 2; ++k) dst[n][k] = *(const PG8_LAS bf16x8*)(lds + PG8_SB(b, h) + boff + n * 2048 + k * 1024); } while (0)
; #define PG8_MMA(ai, bj, At, Bt) do { __builtin_amdgcn_s_setprio(1); _Pragma("unroll") for (int m = 0; m < 4; ++m) _Pragma("unroll") for (int n = 0; n < 2; ++n) _Pragma("unroll") for (int k = 0; k < 2; ++k) \
;         acc[ai][bj][m][n] = __builtin_amdgcn_mfma_f32_16x16x32_bf16(Bt[n][k], At[m][k], acc[ai][bj][m][n], 0, 0, 0); __builtin_amdgcn_s_setprio(0); } while (0)
; #define PG8_WAIT_V(n) asm volatile("s_waitcnt vmcnt(" #n ")" ::: "memory")
; #define PG8_WAIT_L(n) asm volatile("s_waitcnt lgkmcnt(" #n ")" ::: "memory")
; #define PG8_BAR __builtin_amdgcn_s_barrier()
; #define PG8_SCHED __builtin_amdgcn_sched_barrier(0)
; template <class Epi, class Sched, bool ALIGN_EPI = false, bool SP2 = false>
; __device__ __forceinline__ void gemm_phase(PG8_LAS unsigned char* lds, const Gemm g, const Sched& S, const Epi& E, int tid_in) {
;     ...
;             PG8_LDB(B0, 1, 0); PG8_LDB(B1, 1, 1); PG8_SCHED; PG8_LDA(At, 1, 0); PG8_STAGE(PG8_SA(0, 1), a2 + hstepA, voffA);
;             PG8_WAIT_V(8); PG8_WAIT_L(0); PG8_BAR; PG8_MMA(0, 0, At, B0); PG8_MMA(0, 1, At, B1); PG8_BAR; PG8_SCHED;
;             PG8_LDA(At, 1, 1); PG8_STAGE(PG8_SB(1, 0), b3, voffB); PG8_STAGE(PG8_SB(1, 1), b3 + hstep, voffB); PG8_STAGE(PG8_SA(1, 0), a3, voffA);
;             PG8_WAIT_V(8); PG8_WAIT_L(0); PG8_BAR; PG8_MMA(1, 0, At, B0); PG8_MMA(1, 1, At, B1); PG8_BAR; PG8_SCHED;
;     ...
;         if constexpr (ALIGN_EPI) { if (wr == 0) PG8_BAR; }
	s_add_i32 s58, 0, 0x18000
	v_add_u32_e32 v142, s58, v145
	s_add_i32 s59, 0, 0x1c000
	ds_read_b128 v[148:151], v142
	ds_read_b128 v[152:155], v142 offset:1024
	ds_read_b128 v[156:159], v142 offset:2048
	ds_read_b128 v[160:163], v142 offset:3072
	v_add_u32_e32 v142, s59, v145
	ds_read_b128 v[164:167], v142
	ds_read_b128 v[168:171], v142 offset:1024
	ds_read_b128 v[172:175], v142 offset:2048
	ds_read_b128 v[176:179], v142 offset:3072
	s_add_u32 s14, s14, 0x40000
	s_addc_u32 s15, s15, 0
	s_mov_b32 m0, s47
	ds_read_b128 v[180:183], v146 offset:32768
	ds_read_b128 v[184:187], v146 offset:33792
	ds_read_b128 v[200:203], v146 offset:34816
	ds_read_b128 v[204:207], v146 offset:35840
	ds_read_b128 v[208:211], v146 offset:36864
	ds_read_b128 v[212:215], v146 offset:37888
	ds_read_b128 v[216:219], v146 offset:38912
	ds_read_b128 v[226:229], v146 offset:39936
	global_load_lds_dwordx4 v134, s[14:15]
	s_mov_b32 m0, s49
	s_nop 0
	global_load_lds_dwordx4 v130, s[14:15]
	s_waitcnt vmcnt(8)
	s_waitcnt lgkmcnt(0)
	s_barrier
	s_setprio 1
	s_waitcnt lgkmcnt(0)
	v_mfma_f32_16x16x32_bf16 v[124:127], v[148:151], v[180:183], v[124:127]
	v_mfma_f32_16x16x32_bf16 v[116:119], v[156:159], v[180:183], v[116:119]
	v_mfma_f32_16x16x32_bf16 v[108:111], v[148:151], v[200:203], v[108:111]
	v_mfma_f32_16x16x32_bf16 v[100:103], v[156:159], v[200:203], v[100:103]
	v_mfma_f32_16x16x32_bf16 v[92:95], v[148:151], v[208:211], v[92:95]
	v_mfma_f32_16x16x32_bf16 v[84:87], v[156:159], v[208:211], v[84:87]
	v_mfma_f32_16x16x32_bf16 v[76:79], v[148:151], v[216:219], v[76:79]
	v_mfma_f32_16x16x32_bf16 v[68:71], v[156:159], v[216:219], v[68:71]
	v_mfma_f32_16x16x32_bf16 v[124:127], v[152:155], v[184:187], v[124:127]
	v_mfma_f32_16x16x32_bf16 v[116:119], v[160:163], v[184:187], v[116:119]
	v_mfma_f32_16x16x32_bf16 v[108:111], v[152:155], v[204:207], v[108:111]
	v_mfma_f32_16x16x32_bf16 v[100:103], v[160:163], v[204:207], v[100:103]
	v_mfma_f32_16x16x32_bf16 v[92:95], v[152:155], v[212:215], v[92:95]
	v_mfma_f32_16x16x32_bf16 v[84:87], v[160:163], v[212:215], v[84:87]
	v_mfma_f32_16x16x32_bf16 v[76:79], v[152:155], v[226:229], v[76:79]
	v_mfma_f32_16x16x32_bf16 v[68:71], v[160:163], v[226:229], v[68:71]
	s_setprio 0
	s_setprio 1
	v_mfma_f32_16x16x32_bf16 v[120:123], v[164:167], v[180:183], v[120:123]
	v_mfma_f32_16x16x32_bf16 v[112:115], v[172:175], v[180:183], v[112:115]
	v_mfma_f32_16x16x32_bf16 v[104:107], v[164:167], v[200:203], v[104:107]
	v_mfma_f32_16x16x32_bf16 v[96:99], v[172:175], v[200:203], v[96:99]
	v_mfma_f32_16x16x32_bf16 v[88:91], v[164:167], v[208:211], v[88:91]
	v_mfma_f32_16x16x32_bf16 v[80:83], v[172:175], v[208:211], v[80:83]
	v_mfma_f32_16x16x32_bf16 v[72:75], v[164:167], v[216:219], v[72:75]
	v_mfma_f32_16x16x32_bf16 v[64:67], v[172:175], v[216:219], v[64:67]
	v_mfma_f32_16x16x32_bf16 v[120:123], v[168:171], v[184:187], v[120:123]
	v_mfma_f32_16x16x32_bf16 v[112:115], v[176:179], v[184:187], v[112:115]
	v_mfma_f32_16x16x32_bf16 v[104:107], v[168:171], v[204:207], v[104:107]
	v_mfma_f32_16x16x32_bf16 v[96:99], v[176:179], v[204:207], v[96:99]
	v_mfma_f32_16x16x32_bf16 v[88:91], v[168:171], v[212:215], v[88:91]
	v_mfma_f32_16x16x32_bf16 v[80:83], v[176:179], v[212:215], v[80:83]
	v_mfma_f32_16x16x32_bf16 v[72:75], v[168:171], v[226:229], v[72:75]
	v_mfma_f32_16x16x32_bf16 v[64:67], v[176:179], v[226:229], v[64:67]
	s_setprio 0
	s_barrier
	s_add_i32 s14, s58, s44
	s_mov_b32 m0, s14
	ds_read_b128 v[180:183], v146 offset:49152
	ds_read_b128 v[184:187], v146 offset:50176
	ds_read_b128 v[200:203], v146 offset:51200
	ds_read_b128 v[204:207], v146 offset:52224
	ds_read_b128 v[208:211], v146 offset:53248
	ds_read_b128 v[212:215], v146 offset:54272
	ds_read_b128 v[216:219], v146 offset:55296
	ds_read_b128 v[226:229], v146 offset:56320
	s_add_u32 s12, s12, 0x80
	s_addc_u32 s13, s13, 0
	global_load_lds_dwordx4 v132, s[12:13]
	s_add_i32 m0, s14, 0x2000
	s_nop 0
	global_load_lds_dwordx4 v128, s[12:13]
	s_add_u32 s12, s12, 0x40000
	s_addc_u32 s13, s13, 0
	s_add_i32 s14, s59, s44
	s_mov_b32 m0, s14
	s_nop 0
	global_load_lds_dwordx4 v132, s[12:13]
	s_add_i32 m0, s14, 0x2000
	s_nop 0
	global_load_lds_dwordx4 v128, s[12:13]
	s_mov_b32 m0, s50
	s_nop 0
	s_add_u32 s100, s100, 0x80
	s_addc_u32 s101, s101, 0
	global_load_lds_dwordx4 v134, s[100:101]
	s_mov_b32 m0, s51
	s_nop 0
	global_load_lds_dwordx4 v130, s[100:101]
	s_waitcnt vmcnt(8)
	s_waitcnt lgkmcnt(0)
	s_barrier
	s_setprio 1
	s_waitcnt lgkmcnt(0)
	v_mfma_f32_16x16x32_bf16 v[60:63], v[148:151], v[180:183], v[60:63]
	v_mfma_f32_16x16x32_bf16 v[52:55], v[156:159], v[180:183], v[52:55]
	v_mfma_f32_16x16x32_bf16 v[44:47], v[148:151], v[200:203], v[44:47]
	v_mfma_f32_16x16x32_bf16 v[36:39], v[156:159], v[200:203], v[36:39]
	v_mfma_f32_16x16x32_bf16 v[28:31], v[148:151], v[208:211], v[28:31]
	v_mfma_f32_16x16x32_bf16 v[20:23], v[156:159], v[208:211], v[20:23]
	v_mfma_f32_16x16x32_bf16 v[12:15], v[148:151], v[216:219], v[12:15]
	v_mfma_f32_16x16x32_bf16 v[4:7], v[156:159], v[216:219], v[4:7]
	v_mfma_f32_16x16x32_bf16 v[60:63], v[152:155], v[184:187], v[60:63]
	v_mfma_f32_16x16x32_bf16 v[52:55], v[160:163], v[184:187], v[52:55]
	v_mfma_f32_16x16x32_bf16 v[44:47], v[152:155], v[204:207], v[44:47]
	v_mfma_f32_16x16x32_bf16 v[36:39], v[160:163], v[204:207], v[36:39]
	v_mfma_f32_16x16x32_bf16 v[28:31], v[152:155], v[212:215], v[28:31]
	v_mfma_f32_16x16x32_bf16 v[20:23], v[160:163], v[212:215], v[20:23]
	v_mfma_f32_16x16x32_bf16 v[12:15], v[152:155], v[226:229], v[12:15]
	v_mfma_f32_16x16x32_bf16 v[4:7], v[160:163], v[226:229], v[4:7]
	s_setprio 0
	s_setprio 1
	v_mfma_f32_16x16x32_bf16 v[56:59], v[164:167], v[180:183], v[56:59]
	v_mfma_f32_16x16x32_bf16 v[48:51], v[172:175], v[180:183], v[48:51]
	v_mfma_f32_16x16x32_bf16 v[40:43], v[164:167], v[200:203], v[40:43]
	v_mfma_f32_16x16x32_bf16 v[32:35], v[172:175], v[200:203], v[32:35]
	v_mfma_f32_16x16x32_bf16 v[24:27], v[164:167], v[208:211], v[24:27]
	v_mfma_f32_16x16x32_bf16 v[16:19], v[172:175], v[208:211], v[16:19]
	v_mfma_f32_16x16x32_bf16 v[8:11], v[164:167], v[216:219], v[8:11]
	v_mfma_f32_16x16x32_bf16 v[0:3], v[172:175], v[216:219], v[0:3]
	v_mfma_f32_16x16x32_bf16 v[56:59], v[168:171], v[184:187], v[56:59]
	v_mfma_f32_16x16x32_bf16 v[48:51], v[176:179], v[184:187], v[48:51]
	v_mfma_f32_16x16x32_bf16 v[40:43], v[168:171], v[204:207], v[40:43]
	v_mfma_f32_16x16x32_bf16 v[32:35], v[176:179], v[204:207], v[32:35]
	v_mfma_f32_16x16x32_bf16 v[24:27], v[168:171], v[212:215], v[24:27]
	v_mfma_f32_16x16x32_bf16 v[16:19], v[176:179], v[212:215], v[16:19]
	v_mfma_f32_16x16x32_bf16 v[8:11], v[168:171], v[226:229], v[8:11]
	v_mfma_f32_16x16x32_bf16 v[0:3], v[176:179], v[226:229], v[0:3]
	s_setprio 0
	s_barrier
	s_add_i32 s57, s57, 2
	s_add_u32 s55, s55, 0x100
	s_addc_u32 s56, s56, 0
	s_add_u32 s2, s2, 0x100
	s_addc_u32 s3, s3, 0
	s_cmp_gt_u32 s57, 13
	s_cbranch_scc0 .LBB0_1385
	s_and_b64 vcc, exec, s[10:11]
	s_cbranch_vccz .LBB0_1388
	s_barrier

; #define PG8_STAGE(bufoff, gbase, voff) do { _Pragma("unroll") for (int _i = 0; _i < 2; ++_i) \
;         __builtin_amdgcn_global_load_lds((const unsigned*)((const char*)(gbase) + (voff)[_i]), (PG8_LAS unsigned*)(lds + (bufoff) + ldsw + _i * 8192), 16, 0, 0); } while (0)
; #define PG8_LDA(dst, b, h) do { _Pragma("unroll") for (int m = 0; m < 4; ++m) _Pragma("unroll") for (int k = 0; k < 2; ++k) dst[m][k] = *(const PG8_LAS bf16x8*)(lds + PG8_SA(b, h) + aoff + m * 2048 + k * 1024); } while (0)
; #define PG8_LDB(dst, b, h) do { _Pragma("unroll") for (int n = 0; n < 2; ++n) _Pragma("unroll") for (int k = 0; k < 2; ++k) dst[n][k] = *(const PG8_LAS bf16x8*)(lds + PG8_SB(b, h) + boff + n * 2048 + k * 1024); } while (0)
; #define PG8_MMA(ai, bj, At, Bt) do { __builtin_amdgcn_s_setprio(1); _Pragma("unroll") for (int m = 0; m < 4; ++m) _Pragma("unroll") for (int n = 0; n < 2; ++n) _Pragma("unroll") for (int k = 0; k < 2; ++k) \
;         acc[ai][bj][m][n] = __builtin_amdgcn_mfma_f32_16x16x32_bf16(Bt[n][k], At[m][k], acc[ai][bj][m][n], 0, 0, 0); __builtin_amdgcn_s_setprio(0); } while (0)
; #define PG8_WAIT_V(n) asm volatile("s_waitcnt vmcnt(" #n ")" ::: "memory")
; #define PG8_WAIT_L(n) asm volatile("s_waitcnt lgkmcnt(" #n ")" ::: "memory")
; #define PG8_BAR __builtin_amdgcn_s_barrier()
; #define PG8_SCHED __builtin_amdgcn_sched_barrier(0)
; template <class Epi, class Sched, bool ALIGN_EPI = false, bool SP2 = false>
; __device__ __forceinline__ void gemm_phase(PG8_LAS unsigned char* lds, const Gemm g, const Sched& S, const Epi& E, int tid_in) {
;     ...
;             const bool last = (t == nt - 2);
;             const char* a1 = cA + (size_t)(t + 1) * kstep;
;             const char* a2 = last ? nA : cA + (size_t)(t + 2) * kstep; const char* b2 = last ? nB : cB + (size_t)(t + 2) * kstep;
;             const char* a3 = a2 + kstep; const char* b3 = b2 + kstep;
;             if (last && has_next) S.a_ready(nxt);
;             if constexpr (SP2) {
;             PG8_LDB(B0, 0, 0); PG8_LDB(B1, 0, 1); PG8_SCHED; PG8_LDA(At, 0, 0); PG8_STAGE(PG8_SA(1, 1), a1 + hstepA, voffA);
;             PG8_WAIT_V(8); PG8_WAIT_L(0); PG8_BAR; PG8_MMA(0, 0, At, B0); PG8_MMA(0, 1, At, B1); PG8_BAR; PG8_SCHED;
;             PG8_LDA(At, 0, 1); PG8_STAGE(PG8_SB(0, 0), b2, voffB); PG8_STAGE(PG8_SB(0, 1), b2 + hstep, voffB); PG8_STAGE(PG8_SA(0, 0), a2, voffA);
.LBB0_1479:
	s_add_u32 s14, s12, 0x100
	s_addc_u32 s15, s13, 0
	s_add_i32 s56, 0, 0x10000
	s_cmp_eq_u32 s55, 40
	s_cselect_b32 s25, s11, s15
	s_cselect_b32 s24, s10, s14
	s_cselect_b32 s21, s19, s45
	s_cselect_b32 s20, s18, s44
	s_add_i32 s57, 0, 0x14000
	v_add_u32_e32 v124, s56, v226
	v_add_u32_e32 v140, s57, v226
	ds_read_b128 v[112:115], v124
	ds_read_b128 v[116:119], v124 offset:1024
	ds_read_b128 v[120:123], v124 offset:2048
	ds_read_b128 v[124:127], v124 offset:3072
	ds_read_b128 v[128:131], v140
	ds_read_b128 v[132:135], v140 offset:1024
	ds_read_b128 v[136:139], v140 offset:2048
	ds_read_b128 v[140:143], v140 offset:3072
	s_add_i32 m0, s31, 0xc000
	ds_read_b128 v[144:147], v227
	ds_read_b128 v[148:151], v227 offset:1024
	ds_read_b128 v[152:155], v227 offset:2048
	ds_read_b128 v[156:159], v227 offset:3072
	ds_read_b128 v[176:179], v227 offset:4096
	ds_read_b128 v[180:183], v227 offset:5120
	ds_read_b128 v[208:211], v227 offset:6144
	ds_read_b128 v[212:215], v227 offset:7168
	global_load_lds_dwordx4 v206, s[12:13]
	s_add_i32 m0, s31, 0xe000
	s_nop 0
	global_load_lds_dwordx4 v204, s[12:13]
	s_waitcnt vmcnt(8)
	s_waitcnt lgkmcnt(0)
	s_barrier
	s_setprio 1
	s_waitcnt lgkmcnt(0)
	v_mfma_f32_16x16x32_bf16 v[172:175], v[112:115], v[144:147], v[172:175]
	v_mfma_f32_16x16x32_bf16 v[168:171], v[120:123], v[144:147], v[168:171]
	v_mfma_f32_16x16x32_bf16 v[108:111], v[112:115], v[152:155], v[108:111]
	v_mfma_f32_16x16x32_bf16 v[104:107], v[120:123], v[152:155], v[104:107]
	v_mfma_f32_16x16x32_bf16 v[92:95], v[112:115], v[176:179], v[92:95]
	v_mfma_f32_16x16x32_bf16 v[88:91], v[120:123], v[176:179], v[88:91]
	v_mfma_f32_16x16x32_bf16 v[76:79], v[112:115], v[208:211], v[76:79]
	v_mfma_f32_16x16x32_bf16 v[72:75], v[120:123], v[208:211], v[72:75]
	v_mfma_f32_16x16x32_bf16 v[172:175], v[116:119], v[148:151], v[172:175]
	v_mfma_f32_16x16x32_bf16 v[168:171], v[124:127], v[148:151], v[168:171]
	v_mfma_f32_16x16x32_bf16 v[108:111], v[116:119], v[156:159], v[108:111]
	v_mfma_f32_16x16x32_bf16 v[104:107], v[124:127], v[156:159], v[104:107]
	v_mfma_f32_16x16x32_bf16 v[92:95], v[116:119], v[180:183], v[92:95]
	v_mfma_f32_16x16x32_bf16 v[88:91], v[124:127], v[180:183], v[88:91]
	v_mfma_f32_16x16x32_bf16 v[76:79], v[116:119], v[212:215], v[76:79]
	v_mfma_f32_16x16x32_bf16 v[72:75], v[124:127], v[212:215], v[72:75]
	s_setprio 0
	s_setprio 1
	v_mfma_f32_16x16x32_bf16 v[164:167], v[128:131], v[144:147], v[164:167]
	v_mfma_f32_16x16x32_bf16 v[100:103], v[128:131], v[152:155], v[100:103]
	v_mfma_f32_16x16x32_bf16 v[96:99], v[136:139], v[152:155], v[96:99]
	v_mfma_f32_16x16x32_bf16 v[84:87], v[128:131], v[176:179], v[84:87]
	v_mfma_f32_16x16x32_bf16 v[80:83], v[136:139], v[176:179], v[80:83]
	v_mfma_f32_16x16x32_bf16 v[68:71], v[128:131], v[208:211], v[68:71]
	v_mfma_f32_16x16x32_bf16 v[64:67], v[136:139], v[208:211], v[64:67]
	v_mfma_f32_16x16x32_bf16 v[164:167], v[132:135], v[148:151], v[164:167]
	v_mfma_f32_16x16x32_bf16 v[144:147], v[136:139], v[144:147], v[160:163]
	v_mfma_f32_16x16x32_bf16 v[100:103], v[132:135], v[156:159], v[100:103]
	v_mfma_f32_16x16x32_bf16 v[96:99], v[140:143], v[156:159], v[96:99]
	v_mfma_f32_16x16x32_bf16 v[84:87], v[132:135], v[180:183], v[84:87]
	v_mfma_f32_16x16x32_bf16 v[80:83], v[140:143], v[180:183], v[80:83]
	v_mfma_f32_16x16x32_bf16 v[68:71], v[132:135], v[212:215], v[68:71]
	v_mfma_f32_16x16x32_bf16 v[64:67], v[140:143], v[212:215], v[64:67]
	v_mfma_f32_16x16x32_bf16 v[144:147], v[140:143], v[148:151], v[144:147]
	s_setprio 0
	s_barrier
	s_add_i32 s12, s56, s30
	s_mov_b64 s[100:101], s[20:21]
	s_mov_b32 m0, s12
	ds_read_b128 v[148:151], v227 offset:16384
	ds_read_b128 v[152:155], v227 offset:17408
	ds_read_b128 v[156:159], v227 offset:18432
	ds_read_b128 v[160:163], v227 offset:19456
	ds_read_b128 v[176:179], v227 offset:20480
	ds_read_b128 v[180:183], v227 offset:21504
	ds_read_b128 v[208:211], v227 offset:22528
	ds_read_b128 v[212:215], v227 offset:23552
	global_load_lds_dwordx4 v190, s[100:101]
	s_add_i32 m0, s12, 0x2000
	s_add_u32 s12, s20, 0xb0000
	s_addc_u32 s13, s21, 0
	s_add_i32 s56, s57, s30
	global_load_lds_dwordx4 v184, s[100:101]
	s_mov_b32 m0, s56
	v_lshl_add_u64 v[232:233], s[24:25], 0, v[188:189]
	global_load_lds_dwordx4 v190, s[12:13]
	s_add_i32 m0, s56, 0x2000
	v_lshl_add_u64 v[234:235], s[24:25], 0, v[186:187]
	global_load_lds_dwordx4 v184, s[12:13]
	s_mov_b32 m0, s31
	s_nop 0
	global_load_lds_dwordx4 v[232:233], off
	s_mov_b32 m0, s34
	s_nop 0
	global_load_lds_dwordx4 v[234:235], off
	s_waitcnt vmcnt(8)
	s_waitcnt lgkmcnt(0)
	s_barrier
; #define PG8_STAGE(bufoff, gbase, voff) do { _Pragma("unroll") for (int _i = 0; _i < 2; ++_i) \
;         __builtin_amdgcn_global_load_lds((const unsigned*)((const char*)(gbase) + (voff)[_i]), (PG8_LAS unsigned*)(lds + (bufoff) + ldsw + _i * 8192), 16, 0, 0); } while (0)
; #define PG8_LDA(dst, b, h) do { _Pragma("unroll") for (int m = 0; m < 4; ++m) _Pragma("unroll") for (int k = 0; k < 2; ++k) dst[m][k] = *(const PG8_LAS bf16x8*)(lds + PG8_SA(b, h) + aoff + m * 2048 + k * 1024); } while (0)
; #define PG8_LDB(dst, b, h) do { _Pragma("unroll") for (int n = 0; n < 2; ++n) _Pragma("unroll") for (int k = 0; k < 2; ++k) dst[n][k] = *(const PG8_LAS bf16x8*)(lds + PG8_SB(b, h) + boff + n * 2048 + k * 1024); } while (0)
; #define PG8_MMA(ai, bj, At, Bt) do { __builtin_amdgcn_s_setprio(1); _Pragma("unroll") for (int m = 0; m < 4; ++m) _Pragma("unroll") for (int n = 0; n < 2; ++n) _Pragma("unroll") for (int k = 0; k < 2; ++k) \
;         acc[ai][bj][m][n] = __builtin_amdgcn_mfma_f32_16x16x32_bf16(Bt[n][k], At[m][k], acc[ai][bj][m][n], 0, 0, 0); __builtin_amdgcn_s_setprio(0); } while (0)
; #define PG8_WAIT_V(n) asm volatile("s_waitcnt vmcnt(" #n ")" ::: "memory")
; #define PG8_WAIT_L(n) asm volatile("s_waitcnt lgkmcnt(" #n ")" ::: "memory")
; #define PG8_BAR __builtin_amdgcn_s_barrier()
; #define PG8_SCHED __builtin_amdgcn_sched_barrier(0)
; template <class Epi, class Sched, bool ALIGN_EPI = false, bool SP2 = false>
; __device__ __forceinline__ void gemm_phase(PG8_LAS unsigned char* lds, const Gemm g, const Sched& S, const Epi& E, int tid_in) {
;     ...
;             PG8_WAIT_V(8); PG8_WAIT_L(0); PG8_BAR; PG8_MMA(1, 0, At, B0); PG8_MMA(1, 1, At, B1); PG8_BAR; PG8_SCHED;
;             PG8_LDB(B0, 1, 0); PG8_LDB(B1, 1, 1); PG8_SCHED; PG8_LDA(At, 1, 0); PG8_STAGE(PG8_SA(0, 1), a2 + hstepA, voffA);
;             PG8_WAIT_V(8); PG8_WAIT_L(0); PG8_BAR; PG8_MMA(0, 0, At, B0); PG8_MMA(0, 1, At, B1); PG8_BAR; PG8_SCHED;
	s_setprio 1
	s_waitcnt lgkmcnt(0)
	v_mfma_f32_16x16x32_bf16 v[60:63], v[112:115], v[148:151], v[60:63]
	v_mfma_f32_16x16x32_bf16 v[56:59], v[120:123], v[148:151], v[56:59]
	v_mfma_f32_16x16x32_bf16 v[44:47], v[112:115], v[156:159], v[44:47]
	v_mfma_f32_16x16x32_bf16 v[40:43], v[120:123], v[156:159], v[40:43]
	v_mfma_f32_16x16x32_bf16 v[28:31], v[112:115], v[176:179], v[28:31]
	v_mfma_f32_16x16x32_bf16 v[24:27], v[120:123], v[176:179], v[24:27]
	v_mfma_f32_16x16x32_bf16 v[12:15], v[112:115], v[208:211], v[12:15]
	v_mfma_f32_16x16x32_bf16 v[8:11], v[120:123], v[208:211], v[8:11]
	v_mfma_f32_16x16x32_bf16 v[60:63], v[116:119], v[152:155], v[60:63]
	v_mfma_f32_16x16x32_bf16 v[56:59], v[124:127], v[152:155], v[56:59]
	v_mfma_f32_16x16x32_bf16 v[44:47], v[116:119], v[160:163], v[44:47]
	v_mfma_f32_16x16x32_bf16 v[40:43], v[124:127], v[160:163], v[40:43]
	v_mfma_f32_16x16x32_bf16 v[28:31], v[116:119], v[180:183], v[28:31]
	v_mfma_f32_16x16x32_bf16 v[24:27], v[124:127], v[180:183], v[24:27]
	v_mfma_f32_16x16x32_bf16 v[12:15], v[116:119], v[212:215], v[12:15]
	v_mfma_f32_16x16x32_bf16 v[8:11], v[124:127], v[212:215], v[8:11]
	s_setprio 0
	s_setprio 1
	v_mfma_f32_16x16x32_bf16 v[52:55], v[128:131], v[148:151], v[52:55]
	v_mfma_f32_16x16x32_bf16 v[48:51], v[136:139], v[148:151], v[48:51]
	v_mfma_f32_16x16x32_bf16 v[36:39], v[128:131], v[156:159], v[36:39]
	v_mfma_f32_16x16x32_bf16 v[32:35], v[136:139], v[156:159], v[32:35]
	v_mfma_f32_16x16x32_bf16 v[20:23], v[128:131], v[176:179], v[20:23]
	v_mfma_f32_16x16x32_bf16 v[16:19], v[136:139], v[176:179], v[16:19]
	v_mfma_f32_16x16x32_bf16 v[4:7], v[128:131], v[208:211], v[4:7]
	v_mfma_f32_16x16x32_bf16 v[0:3], v[136:139], v[208:211], v[0:3]
	v_mfma_f32_16x16x32_bf16 v[52:55], v[132:135], v[152:155], v[52:55]
	v_mfma_f32_16x16x32_bf16 v[48:51], v[140:143], v[152:155], v[48:51]
	v_mfma_f32_16x16x32_bf16 v[36:39], v[132:135], v[160:163], v[36:39]
	v_mfma_f32_16x16x32_bf16 v[32:35], v[140:143], v[160:163], v[32:35]
	v_mfma_f32_16x16x32_bf16 v[20:23], v[132:135], v[180:183], v[20:23]
	v_mfma_f32_16x16x32_bf16 v[16:19], v[140:143], v[180:183], v[16:19]
	v_mfma_f32_16x16x32_bf16 v[4:7], v[132:135], v[212:215], v[4:7]
	v_mfma_f32_16x16x32_bf16 v[0:3], v[140:143], v[212:215], v[0:3]
	s_setprio 0
	s_barrier
	s_add_i32 s56, 0, 0x18000
	s_add_i32 s57, 0, 0x1c000
	v_add_u32_e32 v124, s56, v226
	v_add_u32_e32 v140, s57, v226
	ds_read_b128 v[112:115], v124
	ds_read_b128 v[116:119], v124 offset:1024
	ds_read_b128 v[120:123], v124 offset:2048
	ds_read_b128 v[124:127], v124 offset:3072
	ds_read_b128 v[128:131], v140
	ds_read_b128 v[132:135], v140 offset:1024
	ds_read_b128 v[136:139], v140 offset:2048
	ds_read_b128 v[140:143], v140 offset:3072
	s_add_u32 s12, s24, 0xb0000
	s_addc_u32 s13, s25, 0
	s_mov_b32 m0, s35
	ds_read_b128 v[148:151], v227 offset:32768
	ds_read_b128 v[152:155], v227 offset:33792
	ds_read_b128 v[156:159], v227 offset:34816
	ds_read_b128 v[176:179], v227 offset:35840
	ds_read_b128 v[180:183], v227 offset:36864
	ds_read_b128 v[208:211], v227 offset:37888
	ds_read_b128 v[212:215], v227 offset:38912
	ds_read_b128 v[216:219], v227 offset:39936
	global_load_lds_dwordx4 v188, s[12:13]
	s_mov_b32 m0, s46
	s_nop 0
	global_load_lds_dwordx4 v186, s[12:13]
	s_waitcnt vmcnt(8)
	s_waitcnt lgkmcnt(0)
	s_barrier
	s_setprio 1
	s_waitcnt lgkmcnt(0)
	v_mfma_f32_16x16x32_bf16 v[160:163], v[112:115], v[148:151], v[172:175]
	v_mfma_f32_16x16x32_bf16 v[172:175], v[116:119], v[152:155], v[160:163]
	v_mfma_f32_16x16x32_bf16 v[160:163], v[120:123], v[148:151], v[168:171]
	v_mfma_f32_16x16x32_bf16 v[108:111], v[112:115], v[156:159], v[108:111]
	v_mfma_f32_16x16x32_bf16 v[104:107], v[120:123], v[156:159], v[104:107]
	v_mfma_f32_16x16x32_bf16 v[92:95], v[112:115], v[180:183], v[92:95]
	v_mfma_f32_16x16x32_bf16 v[88:91], v[120:123], v[180:183], v[88:91]
	v_mfma_f32_16x16x32_bf16 v[76:79], v[112:115], v[212:215], v[76:79]
	v_mfma_f32_16x16x32_bf16 v[72:75], v[120:123], v[212:215], v[72:75]
	v_mfma_f32_16x16x32_bf16 v[168:171], v[124:127], v[152:155], v[160:163]
	v_mfma_f32_16x16x32_bf16 v[108:111], v[116:119], v[176:179], v[108:111]
	v_mfma_f32_16x16x32_bf16 v[104:107], v[124:127], v[176:179], v[104:107]
	v_mfma_f32_16x16x32_bf16 v[92:95], v[116:119], v[208:211], v[92:95]
	v_mfma_f32_16x16x32_bf16 v[88:91], v[124:127], v[208:211], v[88:91]
	v_mfma_f32_16x16x32_bf16 v[76:79], v[116:119], v[216:219], v[76:79]
	v_mfma_f32_16x16x32_bf16 v[72:75], v[124:127], v[216:219], v[72:75]
	s_setprio 0
	s_setprio 1
	v_mfma_f32_16x16x32_bf16 v[160:163], v[128:131], v[148:151], v[164:167]
	v_mfma_f32_16x16x32_bf16 v[144:147], v[136:139], v[148:151], v[144:147]
	v_mfma_f32_16x16x32_bf16 v[100:103], v[128:131], v[156:159], v[100:103]
	v_mfma_f32_16x16x32_bf16 v[96:99], v[136:139], v[156:159], v[96:99]
	v_mfma_f32_16x16x32_bf16 v[84:87], v[128:131], v[180:183], v[84:87]
	v_mfma_f32_16x16x32_bf16 v[80:83], v[136:139], v[180:183], v[80:83]
	v_mfma_f32_16x16x32_bf16 v[68:71], v[128:131], v[212:215], v[68:71]
	v_mfma_f32_16x16x32_bf16 v[64:67], v[136:139], v[212:215], v[64:67]
	v_mfma_f32_16x16x32_bf16 v[164:167], v[132:135], v[152:155], v[160:163]
	v_mfma_f32_16x16x32_bf16 v[160:163], v[140:143], v[152:155], v[144:147]
	v_mfma_f32_16x16x32_bf16 v[100:103], v[132:135], v[176:179], v[100:103]
	v_mfma_f32_16x16x32_bf16 v[96:99], v[140:143], v[176:179], v[96:99]
	v_mfma_f32_16x16x32_bf16 v[84:87], v[132:135], v[208:211], v[84:87]
	v_mfma_f32_16x16x32_bf16 v[80:83], v[140:143], v[208:211], v[80:83]
	v_mfma_f32_16x16x32_bf16 v[68:71], v[132:135], v[216:219], v[68:71]
	v_mfma_f32_16x16x32_bf16 v[64:67], v[140:143], v[216:219], v[64:67]
	s_setprio 0
	s_barrier
; #define PG8_STAGE(bufoff, gbase, voff) do { _Pragma("unroll") for (int _i = 0; _i < 2; ++_i) \
;         __builtin_amdgcn_global_load_lds((const unsigned*)((const char*)(gbase) + (voff)[_i]), (PG8_LAS unsigned*)(lds + (bufoff) + ldsw + _i * 8192), 16, 0, 0); } while (0)
; #define PG8_LDA(dst, b, h) do { _Pragma("unroll") for (int m = 0; m < 4; ++m) _Pragma("unroll") for (int k = 0; k < 2; ++k) dst[m][k] = *(const PG8_LAS bf16x8*)(lds + PG8_SA(b, h) + aoff + m * 2048 + k * 1024); } while (0)
; #define PG8_MMA(ai, bj, At, Bt) do { __builtin_amdgcn_s_setprio(1); _Pragma("unroll") for (int m = 0; m < 4; ++m) _Pragma("unroll") for (int n = 0; n < 2; ++n) _Pragma("unroll") for (int k = 0; k < 2; ++k) \
;         acc[ai][bj][m][n] = __builtin_amdgcn_mfma_f32_16x16x32_bf16(Bt[n][k], At[m][k], acc[ai][bj][m][n], 0, 0, 0); __builtin_amdgcn_s_setprio(0); } while (0)
; #define PG8_WAIT_V(n) asm volatile("s_waitcnt vmcnt(" #n ")" ::: "memory")
; #define PG8_WAIT_L(n) asm volatile("s_waitcnt lgkmcnt(" #n ")" ::: "memory")
; #define PG8_BAR __builtin_amdgcn_s_barrier()
; #define PG8_SCHED __builtin_amdgcn_sched_barrier(0)
; template <class Epi, class Sched, bool ALIGN_EPI = false, bool SP2 = false>
; __device__ __forceinline__ void gemm_phase(PG8_LAS unsigned char* lds, const Gemm g, const Sched& S, const Epi& E, int tid_in) {
;     ...
;             PG8_LDA(At, 1, 1); PG8_STAGE(PG8_SB(1, 0), b3, voffB); PG8_STAGE(PG8_SB(1, 1), b3 + hstep, voffB); PG8_STAGE(PG8_SA(1, 0), a3, voffA);
;             PG8_WAIT_V(8); PG8_WAIT_L(0); PG8_BAR; PG8_MMA(1, 0, At, B0); PG8_MMA(1, 1, At, B1); PG8_BAR; PG8_SCHED;
;     ...
;         if constexpr (ALIGN_EPI) { if (wr == 0) PG8_BAR; }
	s_add_i32 s12, s56, s30
	s_mov_b32 m0, s12
	ds_read_b128 v[144:147], v227 offset:49152
	ds_read_b128 v[148:151], v227 offset:50176
	ds_read_b128 v[152:155], v227 offset:51200
	ds_read_b128 v[156:159], v227 offset:52224
	ds_read_b128 v[176:179], v227 offset:53248
	ds_read_b128 v[180:183], v227 offset:54272
	ds_read_b128 v[208:211], v227 offset:55296
	ds_read_b128 v[212:215], v227 offset:56320
	s_add_u32 s100, s100, 0x80
	s_addc_u32 s101, s101, 0
	global_load_lds_dwordx4 v190, s[100:101]
	s_add_i32 m0, s12, 0x2000
	s_add_u32 s12, s20, 0xb0080
	s_addc_u32 s13, s21, 0
	s_add_i32 s20, s57, s30
	global_load_lds_dwordx4 v184, s[100:101]
	s_mov_b32 m0, s20
	s_nop 0
	global_load_lds_dwordx4 v190, s[12:13]
	s_add_i32 m0, s20, 0x2000
	s_nop 0
	global_load_lds_dwordx4 v184, s[12:13]
	v_lshl_add_u64 v[216:217], v[232:233], 0, s[0:1]
	s_mov_b32 m0, s49
	s_nop 0
	global_load_lds_dwordx4 v[216:217], off
	v_lshl_add_u64 v[216:217], v[234:235], 0, s[0:1]
	s_mov_b32 m0, s50
	s_nop 0
	global_load_lds_dwordx4 v[216:217], off
	s_waitcnt vmcnt(8)
	s_waitcnt lgkmcnt(0)
	s_barrier
	s_setprio 1
	s_waitcnt lgkmcnt(0)
	v_mfma_f32_16x16x32_bf16 v[60:63], v[112:115], v[144:147], v[60:63]
	v_mfma_f32_16x16x32_bf16 v[56:59], v[120:123], v[144:147], v[56:59]
	v_mfma_f32_16x16x32_bf16 v[44:47], v[112:115], v[152:155], v[44:47]
	v_mfma_f32_16x16x32_bf16 v[40:43], v[120:123], v[152:155], v[40:43]
	v_mfma_f32_16x16x32_bf16 v[28:31], v[112:115], v[176:179], v[28:31]
	v_mfma_f32_16x16x32_bf16 v[24:27], v[120:123], v[176:179], v[24:27]
	v_mfma_f32_16x16x32_bf16 v[12:15], v[112:115], v[208:211], v[12:15]
	v_mfma_f32_16x16x32_bf16 v[8:11], v[120:123], v[208:211], v[8:11]
	v_mfma_f32_16x16x32_bf16 v[60:63], v[116:119], v[148:151], v[60:63]
	v_mfma_f32_16x16x32_bf16 v[56:59], v[124:127], v[148:151], v[56:59]
	v_mfma_f32_16x16x32_bf16 v[44:47], v[116:119], v[156:159], v[44:47]
	v_mfma_f32_16x16x32_bf16 v[40:43], v[124:127], v[156:159], v[40:43]
	v_mfma_f32_16x16x32_bf16 v[28:31], v[116:119], v[180:183], v[28:31]
	v_mfma_f32_16x16x32_bf16 v[24:27], v[124:127], v[180:183], v[24:27]
	v_mfma_f32_16x16x32_bf16 v[12:15], v[116:119], v[212:215], v[12:15]
	v_mfma_f32_16x16x32_bf16 v[8:11], v[124:127], v[212:215], v[8:11]
	s_setprio 0
	s_setprio 1
	v_mfma_f32_16x16x32_bf16 v[52:55], v[128:131], v[144:147], v[52:55]
	v_mfma_f32_16x16x32_bf16 v[48:51], v[136:139], v[144:147], v[48:51]
	v_mfma_f32_16x16x32_bf16 v[36:39], v[128:131], v[152:155], v[36:39]
	v_mfma_f32_16x16x32_bf16 v[32:35], v[136:139], v[152:155], v[32:35]
	v_mfma_f32_16x16x32_bf16 v[20:23], v[128:131], v[176:179], v[20:23]
	v_mfma_f32_16x16x32_bf16 v[16:19], v[136:139], v[176:179], v[16:19]
	v_mfma_f32_16x16x32_bf16 v[4:7], v[128:131], v[208:211], v[4:7]
	v_mfma_f32_16x16x32_bf16 v[0:3], v[136:139], v[208:211], v[0:3]
	v_mfma_f32_16x16x32_bf16 v[52:55], v[132:135], v[148:151], v[52:55]
	v_mfma_f32_16x16x32_bf16 v[48:51], v[140:143], v[148:151], v[48:51]
	v_mfma_f32_16x16x32_bf16 v[36:39], v[132:135], v[156:159], v[36:39]
	v_mfma_f32_16x16x32_bf16 v[32:35], v[140:143], v[156:159], v[32:35]
	v_mfma_f32_16x16x32_bf16 v[20:23], v[132:135], v[180:183], v[20:23]
	v_mfma_f32_16x16x32_bf16 v[16:19], v[140:143], v[180:183], v[16:19]
	v_mfma_f32_16x16x32_bf16 v[4:7], v[132:135], v[212:215], v[4:7]
	v_mfma_f32_16x16x32_bf16 v[0:3], v[140:143], v[212:215], v[0:3]
	s_setprio 0
	s_barrier
	s_add_i32 s55, s55, 2
	s_add_u32 s44, s44, 0x100
	s_addc_u32 s45, s45, 0
	s_cmp_gt_u32 s55, 41
	s_mov_b64 s[12:13], s[14:15]
	s_cbranch_scc0 .LBB0_1479
	s_and_b64 vcc, exec, s[8:9]
	s_cbranch_vccz .LBB0_1482
	s_barrier
